# GEMM loops: 24 redundant post-barrier lgkmcnt(0) removed, on top of column-group seams + pipelined P5/P8 epilogues + packed SwiGLU epilogue
# speedup vs baseline: 1.0059x; 1.0059x over previous
.LBB0_268:
	ds_read_b128 v[156:159], v151
	ds_read_b128 v[160:163], v151 offset:1024
	ds_read_b128 v[164:167], v151 offset:2048
	ds_read_b128 v[168:171], v151 offset:3072
	ds_read_b128 v[172:175], v152
	ds_read_b128 v[176:179], v152 offset:1024
	ds_read_b128 v[180:183], v152 offset:2048
	ds_read_b128 v[184:187], v152 offset:3072
	s_add_u32 s12, s10, 0xfffc0080
	s_addc_u32 s13, s11, -1
	s_cmp_eq_u32 s46, 12
	s_cselect_b32 s15, s7, s13
	s_cselect_b32 s14, s9, s12
	s_cselect_b32 s13, s27, s45
	s_cselect_b32 s12, s29, s44
	v_lshl_add_u64 v[146:147], s[10:11], 0, v[138:139]
	s_add_i32 m0, s33, 0xc000
	ds_read_b128 v[188:191], v153
	ds_read_b128 v[192:195], v153 offset:1024
	ds_read_b128 v[200:203], v153 offset:2048
	ds_read_b128 v[204:207], v153 offset:3072
	ds_read_b128 v[208:211], v153 offset:4096
	ds_read_b128 v[212:215], v153 offset:5120
	ds_read_b128 v[216:219], v153 offset:6144
	ds_read_b128 v[220:223], v153 offset:7168
	global_load_lds_dwordx4 v[146:147], off
	v_lshl_add_u64 v[146:147], s[10:11], 0, v[140:141]
	s_add_i32 m0, s33, 0xe000
	s_nop 0
	global_load_lds_dwordx4 v[146:147], off
	s_waitcnt vmcnt(8)
	s_waitcnt lgkmcnt(0)
	s_barrier
	s_setprio 1
	v_mfma_f32_16x16x32_bf16 v[120:123], v[156:159], v[188:191], v[120:123]
	v_mfma_f32_16x16x32_bf16 v[124:127], v[164:167], v[188:191], v[124:127]
	v_mfma_f32_16x16x32_bf16 v[104:107], v[156:159], v[200:203], v[104:107]
	v_mfma_f32_16x16x32_bf16 v[108:111], v[164:167], v[200:203], v[108:111]
	v_mfma_f32_16x16x32_bf16 v[88:91], v[156:159], v[208:211], v[88:91]
	v_mfma_f32_16x16x32_bf16 v[92:95], v[164:167], v[208:211], v[92:95]
	v_mfma_f32_16x16x32_bf16 v[72:75], v[156:159], v[216:219], v[72:75]
	v_mfma_f32_16x16x32_bf16 v[76:79], v[164:167], v[216:219], v[76:79]
	v_mfma_f32_16x16x32_bf16 v[120:123], v[160:163], v[192:195], v[120:123]
	v_mfma_f32_16x16x32_bf16 v[124:127], v[168:171], v[192:195], v[124:127]
	v_mfma_f32_16x16x32_bf16 v[104:107], v[160:163], v[204:207], v[104:107]
	v_mfma_f32_16x16x32_bf16 v[108:111], v[168:171], v[204:207], v[108:111]
	v_mfma_f32_16x16x32_bf16 v[88:91], v[160:163], v[212:215], v[88:91]
	v_mfma_f32_16x16x32_bf16 v[92:95], v[168:171], v[212:215], v[92:95]
	v_mfma_f32_16x16x32_bf16 v[72:75], v[160:163], v[220:223], v[72:75]
	v_mfma_f32_16x16x32_bf16 v[76:79], v[168:171], v[220:223], v[76:79]
	s_setprio 0
	s_setprio 1
	v_mfma_f32_16x16x32_bf16 v[112:115], v[172:175], v[188:191], v[112:115]
	v_mfma_f32_16x16x32_bf16 v[116:119], v[180:183], v[188:191], v[116:119]
	v_mfma_f32_16x16x32_bf16 v[96:99], v[172:175], v[200:203], v[96:99]
	v_mfma_f32_16x16x32_bf16 v[100:103], v[180:183], v[200:203], v[100:103]
	v_mfma_f32_16x16x32_bf16 v[80:83], v[172:175], v[208:211], v[80:83]
	v_mfma_f32_16x16x32_bf16 v[84:87], v[180:183], v[208:211], v[84:87]
	v_mfma_f32_16x16x32_bf16 v[64:67], v[172:175], v[216:219], v[64:67]
	v_mfma_f32_16x16x32_bf16 v[68:71], v[180:183], v[216:219], v[68:71]
	v_mfma_f32_16x16x32_bf16 v[112:115], v[176:179], v[192:195], v[112:115]
	v_mfma_f32_16x16x32_bf16 v[116:119], v[184:187], v[192:195], v[116:119]
	v_mfma_f32_16x16x32_bf16 v[96:99], v[176:179], v[204:207], v[96:99]
	v_mfma_f32_16x16x32_bf16 v[100:103], v[184:187], v[204:207], v[100:103]
	v_mfma_f32_16x16x32_bf16 v[80:83], v[176:179], v[212:215], v[80:83]
	v_mfma_f32_16x16x32_bf16 v[84:87], v[184:187], v[212:215], v[84:87]
	v_mfma_f32_16x16x32_bf16 v[64:67], v[176:179], v[220:223], v[64:67]
	v_mfma_f32_16x16x32_bf16 v[68:71], v[184:187], v[220:223], v[68:71]
	s_setprio 0
	s_barrier
	s_add_i32 s47, s67, s25
	v_lshl_add_u64 v[146:147], s[12:13], 0, v[130:131]
	s_mov_b32 m0, s47
	ds_read_b128 v[188:191], v153 offset:16384
	ds_read_b128 v[192:195], v153 offset:17408
	ds_read_b128 v[200:203], v153 offset:18432
	ds_read_b128 v[204:207], v153 offset:19456
	ds_read_b128 v[208:211], v153 offset:20480
	ds_read_b128 v[212:215], v153 offset:21504
	ds_read_b128 v[216:219], v153 offset:22528
	ds_read_b128 v[220:223], v153 offset:23552
	global_load_lds_dwordx4 v[146:147], off
	s_add_i32 m0, s47, 0x2000
	s_add_u32 s48, s12, 0x40000
	v_lshl_add_u64 v[224:225], s[12:13], 0, v[134:135]
	s_addc_u32 s49, s13, 0
	s_add_i32 s47, s68, s25
	global_load_lds_dwordx4 v[224:225], off
	v_lshl_add_u64 v[226:227], s[48:49], 0, v[130:131]
	s_mov_b32 m0, s47
	v_lshl_add_u64 v[228:229], s[14:15], 0, v[132:133]
	global_load_lds_dwordx4 v[226:227], off
	v_lshl_add_u64 v[226:227], s[48:49], 0, v[134:135]
	s_add_i32 m0, s47, 0x2000
	s_nop 0
	global_load_lds_dwordx4 v[226:227], off
	v_lshl_add_u64 v[226:227], s[14:15], 0, v[128:129]
	s_mov_b32 m0, s33
	s_nop 0
	global_load_lds_dwordx4 v[226:227], off
	s_mov_b32 m0, s58
	s_nop 0
	global_load_lds_dwordx4 v[228:229], off
	s_waitcnt vmcnt(8)
	s_waitcnt lgkmcnt(0)
	s_barrier
	s_setprio 1
	v_mfma_f32_16x16x32_bf16 v[56:59], v[156:159], v[188:191], v[56:59]
	v_mfma_f32_16x16x32_bf16 v[60:63], v[164:167], v[188:191], v[60:63]
	v_mfma_f32_16x16x32_bf16 v[40:43], v[156:159], v[200:203], v[40:43]
	v_mfma_f32_16x16x32_bf16 v[44:47], v[164:167], v[200:203], v[44:47]
	v_mfma_f32_16x16x32_bf16 v[24:27], v[156:159], v[208:211], v[24:27]
	v_mfma_f32_16x16x32_bf16 v[28:31], v[164:167], v[208:211], v[28:31]
	v_mfma_f32_16x16x32_bf16 v[8:11], v[156:159], v[216:219], v[8:11]
	v_mfma_f32_16x16x32_bf16 v[12:15], v[164:167], v[216:219], v[12:15]
	v_mfma_f32_16x16x32_bf16 v[56:59], v[160:163], v[192:195], v[56:59]
	v_mfma_f32_16x16x32_bf16 v[60:63], v[168:171], v[192:195], v[60:63]
	v_mfma_f32_16x16x32_bf16 v[40:43], v[160:163], v[204:207], v[40:43]
	v_mfma_f32_16x16x32_bf16 v[44:47], v[168:171], v[204:207], v[44:47]
	v_mfma_f32_16x16x32_bf16 v[24:27], v[160:163], v[212:215], v[24:27]
	v_mfma_f32_16x16x32_bf16 v[28:31], v[168:171], v[212:215], v[28:31]
	v_mfma_f32_16x16x32_bf16 v[8:11], v[160:163], v[220:223], v[8:11]
	v_mfma_f32_16x16x32_bf16 v[12:15], v[168:171], v[220:223], v[12:15]
	s_setprio 0
	s_setprio 1
	v_mfma_f32_16x16x32_bf16 v[48:51], v[172:175], v[188:191], v[48:51]
	v_mfma_f32_16x16x32_bf16 v[52:55], v[180:183], v[188:191], v[52:55]
	v_mfma_f32_16x16x32_bf16 v[32:35], v[172:175], v[200:203], v[32:35]
	v_mfma_f32_16x16x32_bf16 v[36:39], v[180:183], v[200:203], v[36:39]
	v_mfma_f32_16x16x32_bf16 v[16:19], v[172:175], v[208:211], v[16:19]
	v_mfma_f32_16x16x32_bf16 v[20:23], v[180:183], v[208:211], v[20:23]
	v_mfma_f32_16x16x32_bf16 v[4:7], v[172:175], v[216:219], v[4:7]
	v_mfma_f32_16x16x32_bf16 v[0:3], v[180:183], v[216:219], v[0:3]
	v_mfma_f32_16x16x32_bf16 v[48:51], v[176:179], v[192:195], v[48:51]
	v_mfma_f32_16x16x32_bf16 v[52:55], v[184:187], v[192:195], v[52:55]
	v_mfma_f32_16x16x32_bf16 v[32:35], v[176:179], v[204:207], v[32:35]
	v_mfma_f32_16x16x32_bf16 v[36:39], v[184:187], v[204:207], v[36:39]
	v_mfma_f32_16x16x32_bf16 v[16:19], v[176:179], v[212:215], v[16:19]
	v_mfma_f32_16x16x32_bf16 v[20:23], v[184:187], v[212:215], v[20:23]
	v_mfma_f32_16x16x32_bf16 v[4:7], v[176:179], v[220:223], v[4:7]
	v_mfma_f32_16x16x32_bf16 v[0:3], v[184:187], v[220:223], v[0:3]
	s_setprio 0
	s_barrier
	s_add_i32 s47, 0, 0x18000
	v_add_u32_e32 v155, s47, v149
	s_add_i32 s48, 0, 0x1c000
	ds_read_b128 v[156:159], v155
	ds_read_b128 v[160:163], v155 offset:1024
	ds_read_b128 v[164:167], v155 offset:2048
	ds_read_b128 v[168:171], v155 offset:3072
	v_add_u32_e32 v155, s48, v149
	ds_read_b128 v[172:175], v155
	ds_read_b128 v[176:179], v155 offset:1024
	ds_read_b128 v[180:183], v155 offset:2048
	ds_read_b128 v[184:187], v155 offset:3072
	s_add_u32 s14, s14, 0x40000
	s_addc_u32 s15, s15, 0
	s_mov_b32 m0, s59
	v_lshl_add_u64 v[230:231], s[14:15], 0, v[128:129]
	ds_read_b128 v[188:191], v153 offset:32768
	ds_read_b128 v[192:195], v153 offset:33792
	ds_read_b128 v[200:203], v153 offset:34816
	ds_read_b128 v[204:207], v153 offset:35840
	ds_read_b128 v[208:211], v153 offset:36864
	ds_read_b128 v[212:215], v153 offset:37888
	ds_read_b128 v[216:219], v153 offset:38912
	ds_read_b128 v[220:223], v153 offset:39936
	global_load_lds_dwordx4 v[230:231], off
	v_lshl_add_u64 v[230:231], s[14:15], 0, v[132:133]
	s_mov_b32 m0, s60
	s_nop 0
	global_load_lds_dwordx4 v[230:231], off
	s_waitcnt vmcnt(8)
	s_waitcnt lgkmcnt(0)
	s_barrier
	s_setprio 1
	v_mfma_f32_16x16x32_bf16 v[120:123], v[156:159], v[188:191], v[120:123]
	v_mfma_f32_16x16x32_bf16 v[124:127], v[164:167], v[188:191], v[124:127]
	v_mfma_f32_16x16x32_bf16 v[104:107], v[156:159], v[200:203], v[104:107]
	v_mfma_f32_16x16x32_bf16 v[108:111], v[164:167], v[200:203], v[108:111]
	v_mfma_f32_16x16x32_bf16 v[88:91], v[156:159], v[208:211], v[88:91]
	v_mfma_f32_16x16x32_bf16 v[92:95], v[164:167], v[208:211], v[92:95]
	v_mfma_f32_16x16x32_bf16 v[72:75], v[156:159], v[216:219], v[72:75]
	v_mfma_f32_16x16x32_bf16 v[76:79], v[164:167], v[216:219], v[76:79]
	v_mfma_f32_16x16x32_bf16 v[120:123], v[160:163], v[192:195], v[120:123]
	v_mfma_f32_16x16x32_bf16 v[124:127], v[168:171], v[192:195], v[124:127]
	v_mfma_f32_16x16x32_bf16 v[104:107], v[160:163], v[204:207], v[104:107]
	v_mfma_f32_16x16x32_bf16 v[108:111], v[168:171], v[204:207], v[108:111]
	v_mfma_f32_16x16x32_bf16 v[88:91], v[160:163], v[212:215], v[88:91]
	v_mfma_f32_16x16x32_bf16 v[92:95], v[168:171], v[212:215], v[92:95]
	v_mfma_f32_16x16x32_bf16 v[72:75], v[160:163], v[220:223], v[72:75]
	v_mfma_f32_16x16x32_bf16 v[76:79], v[168:171], v[220:223], v[76:79]
	s_setprio 0
	s_setprio 1
	v_mfma_f32_16x16x32_bf16 v[112:115], v[172:175], v[188:191], v[112:115]
	v_mfma_f32_16x16x32_bf16 v[116:119], v[180:183], v[188:191], v[116:119]
	v_mfma_f32_16x16x32_bf16 v[96:99], v[172:175], v[200:203], v[96:99]
	v_mfma_f32_16x16x32_bf16 v[100:103], v[180:183], v[200:203], v[100:103]
	v_mfma_f32_16x16x32_bf16 v[80:83], v[172:175], v[208:211], v[80:83]
	v_mfma_f32_16x16x32_bf16 v[84:87], v[180:183], v[208:211], v[84:87]
	v_mfma_f32_16x16x32_bf16 v[64:67], v[172:175], v[216:219], v[64:67]
	v_mfma_f32_16x16x32_bf16 v[68:71], v[180:183], v[216:219], v[68:71]
	v_mfma_f32_16x16x32_bf16 v[112:115], v[176:179], v[192:195], v[112:115]
	v_mfma_f32_16x16x32_bf16 v[116:119], v[184:187], v[192:195], v[116:119]
	v_mfma_f32_16x16x32_bf16 v[96:99], v[176:179], v[204:207], v[96:99]
	v_mfma_f32_16x16x32_bf16 v[100:103], v[184:187], v[204:207], v[100:103]
	v_mfma_f32_16x16x32_bf16 v[80:83], v[176:179], v[212:215], v[80:83]
	v_mfma_f32_16x16x32_bf16 v[84:87], v[184:187], v[212:215], v[84:87]
	v_mfma_f32_16x16x32_bf16 v[64:67], v[176:179], v[220:223], v[64:67]
	v_mfma_f32_16x16x32_bf16 v[68:71], v[184:187], v[220:223], v[68:71]
	s_setprio 0
	s_barrier
	s_add_i32 s14, s47, s25
	v_lshl_add_u64 v[146:147], v[146:147], 0, s[20:21]
	s_mov_b32 m0, s14
	ds_read_b128 v[188:191], v153 offset:49152
	ds_read_b128 v[192:195], v153 offset:50176
	ds_read_b128 v[200:203], v153 offset:51200
	ds_read_b128 v[204:207], v153 offset:52224
	ds_read_b128 v[208:211], v153 offset:53248
	ds_read_b128 v[212:215], v153 offset:54272
	ds_read_b128 v[216:219], v153 offset:55296
	ds_read_b128 v[220:223], v153 offset:56320
	global_load_lds_dwordx4 v[146:147], off
	s_add_i32 m0, s14, 0x2000
	s_add_u32 s12, s12, 0x40080
	v_lshl_add_u64 v[146:147], v[224:225], 0, s[20:21]
	s_addc_u32 s13, s13, 0
	s_add_i32 s14, s48, s25
	global_load_lds_dwordx4 v[146:147], off
	v_lshl_add_u64 v[146:147], s[12:13], 0, v[130:131]
	s_mov_b32 m0, s14
	s_nop 0
	global_load_lds_dwordx4 v[146:147], off
	v_lshl_add_u64 v[146:147], s[12:13], 0, v[134:135]
	s_add_i32 m0, s14, 0x2000
	s_nop 0
	global_load_lds_dwordx4 v[146:147], off
	v_lshl_add_u64 v[146:147], v[226:227], 0, s[20:21]
	s_mov_b32 m0, s62
	s_nop 0
	global_load_lds_dwordx4 v[146:147], off
	v_lshl_add_u64 v[146:147], v[228:229], 0, s[20:21]
	s_mov_b32 m0, s63
	s_nop 0
	global_load_lds_dwordx4 v[146:147], off
	s_waitcnt vmcnt(8)
	s_waitcnt lgkmcnt(0)
	s_barrier
	s_setprio 1
	v_mfma_f32_16x16x32_bf16 v[56:59], v[156:159], v[188:191], v[56:59]
	v_mfma_f32_16x16x32_bf16 v[60:63], v[164:167], v[188:191], v[60:63]
	v_mfma_f32_16x16x32_bf16 v[40:43], v[156:159], v[200:203], v[40:43]
	v_mfma_f32_16x16x32_bf16 v[44:47], v[164:167], v[200:203], v[44:47]
	v_mfma_f32_16x16x32_bf16 v[24:27], v[156:159], v[208:211], v[24:27]
	v_mfma_f32_16x16x32_bf16 v[28:31], v[164:167], v[208:211], v[28:31]
	v_mfma_f32_16x16x32_bf16 v[8:11], v[156:159], v[216:219], v[8:11]
	v_mfma_f32_16x16x32_bf16 v[12:15], v[164:167], v[216:219], v[12:15]
	v_mfma_f32_16x16x32_bf16 v[56:59], v[160:163], v[192:195], v[56:59]
	v_mfma_f32_16x16x32_bf16 v[60:63], v[168:171], v[192:195], v[60:63]
	v_mfma_f32_16x16x32_bf16 v[40:43], v[160:163], v[204:207], v[40:43]
	v_mfma_f32_16x16x32_bf16 v[44:47], v[168:171], v[204:207], v[44:47]
	v_mfma_f32_16x16x32_bf16 v[24:27], v[160:163], v[212:215], v[24:27]
	v_mfma_f32_16x16x32_bf16 v[28:31], v[168:171], v[212:215], v[28:31]
	v_mfma_f32_16x16x32_bf16 v[8:11], v[160:163], v[220:223], v[8:11]
	v_mfma_f32_16x16x32_bf16 v[12:15], v[168:171], v[220:223], v[12:15]
	s_setprio 0
	s_setprio 1
	v_mfma_f32_16x16x32_bf16 v[48:51], v[172:175], v[188:191], v[48:51]
	v_mfma_f32_16x16x32_bf16 v[52:55], v[180:183], v[188:191], v[52:55]
	v_mfma_f32_16x16x32_bf16 v[32:35], v[172:175], v[200:203], v[32:35]
	v_mfma_f32_16x16x32_bf16 v[36:39], v[180:183], v[200:203], v[36:39]
	v_mfma_f32_16x16x32_bf16 v[16:19], v[172:175], v[208:211], v[16:19]
	v_mfma_f32_16x16x32_bf16 v[20:23], v[180:183], v[208:211], v[20:23]
	v_mfma_f32_16x16x32_bf16 v[4:7], v[172:175], v[216:219], v[4:7]
	v_mfma_f32_16x16x32_bf16 v[0:3], v[180:183], v[216:219], v[0:3]
	v_mfma_f32_16x16x32_bf16 v[48:51], v[176:179], v[192:195], v[48:51]
	v_mfma_f32_16x16x32_bf16 v[52:55], v[184:187], v[192:195], v[52:55]
	v_mfma_f32_16x16x32_bf16 v[32:35], v[176:179], v[204:207], v[32:35]
	v_mfma_f32_16x16x32_bf16 v[36:39], v[184:187], v[204:207], v[36:39]
	v_mfma_f32_16x16x32_bf16 v[16:19], v[176:179], v[212:215], v[16:19]
	v_mfma_f32_16x16x32_bf16 v[20:23], v[184:187], v[212:215], v[20:23]
	v_mfma_f32_16x16x32_bf16 v[4:7], v[176:179], v[220:223], v[4:7]
	v_mfma_f32_16x16x32_bf16 v[0:3], v[184:187], v[220:223], v[0:3]
	s_setprio 0
	s_barrier
	s_add_i32 s46, s46, 2
	s_add_u32 s10, s10, 0x100
	s_addc_u32 s11, s11, 0
	s_add_u32 s44, s44, 0x100
	s_addc_u32 s45, s45, 0
	s_cmp_gt_u32 s46, 13
	s_cbranch_scc0 .LBB0_268
	s_and_b64 vcc, exec, s[22:23]
	s_cbranch_vccz .LBB0_271
	s_barrier

.LBB0_424:
	ds_read_b128 v[104:107], v172
	ds_read_b128 v[108:111], v172 offset:1024
	ds_read_b128 v[112:115], v172 offset:2048
	ds_read_b128 v[158:161], v172 offset:3072
	ds_read_b128 v[178:181], v173
	ds_read_b128 v[182:185], v173 offset:1024
	ds_read_b128 v[186:189], v173 offset:2048
	ds_read_b128 v[190:193], v173 offset:3072
	s_add_u32 s4, s0, 0xfff70080
	s_addc_u32 s5, s1, -1
	s_cmp_eq_u32 s69, 2
	s_cselect_b32 s7, s21, s5
	s_cselect_b32 s6, s20, s4
	s_cselect_b32 s5, s23, s68
	s_cselect_b32 s4, s22, s67
	v_lshl_add_u64 v[194:195], s[0:1], 0, v[152:153]
	s_add_i32 m0, s31, 0xc000
	ds_read_b128 v[200:203], v174
	ds_read_b128 v[204:207], v174 offset:1024
	ds_read_b128 v[208:211], v174 offset:2048
	ds_read_b128 v[212:215], v174 offset:3072
	ds_read_b128 v[216:219], v174 offset:4096
	ds_read_b128 v[220:223], v174 offset:5120
	ds_read_b128 v[224:227], v174 offset:6144
	ds_read_b128 v[228:231], v174 offset:7168
	global_load_lds_dwordx4 v[194:195], off
	v_lshl_add_u64 v[194:195], s[0:1], 0, v[154:155]
	s_add_i32 m0, s31, 0xe000
	s_nop 0
	global_load_lds_dwordx4 v[194:195], off
	s_waitcnt vmcnt(8)
	s_waitcnt lgkmcnt(0)
	s_barrier
	s_setprio 1
	v_mfma_f32_16x16x32_bf16 v[136:139], v[104:107], v[200:203], v[136:139]
	v_mfma_f32_16x16x32_bf16 v[132:135], v[112:115], v[200:203], v[132:135]
	v_mfma_f32_16x16x32_bf16 v[120:123], v[104:107], v[208:211], v[120:123]
	v_mfma_f32_16x16x32_bf16 v[116:119], v[112:115], v[208:211], v[116:119]
	v_mfma_f32_16x16x32_bf16 v[92:95], v[104:107], v[216:219], v[92:95]
	v_mfma_f32_16x16x32_bf16 v[88:91], v[112:115], v[216:219], v[88:91]
	v_mfma_f32_16x16x32_bf16 v[76:79], v[104:107], v[224:227], v[76:79]
	v_mfma_f32_16x16x32_bf16 v[72:75], v[112:115], v[224:227], v[72:75]
	v_mfma_f32_16x16x32_bf16 v[136:139], v[108:111], v[204:207], v[136:139]
	v_mfma_f32_16x16x32_bf16 v[132:135], v[158:161], v[204:207], v[132:135]
	v_mfma_f32_16x16x32_bf16 v[120:123], v[108:111], v[212:215], v[120:123]
	v_mfma_f32_16x16x32_bf16 v[116:119], v[158:161], v[212:215], v[116:119]
	v_mfma_f32_16x16x32_bf16 v[92:95], v[108:111], v[220:223], v[92:95]
	v_mfma_f32_16x16x32_bf16 v[88:91], v[158:161], v[220:223], v[88:91]
	v_mfma_f32_16x16x32_bf16 v[76:79], v[108:111], v[228:231], v[76:79]
	v_mfma_f32_16x16x32_bf16 v[72:75], v[158:161], v[228:231], v[72:75]
	s_setprio 0
	s_setprio 1
	v_mfma_f32_16x16x32_bf16 v[128:131], v[178:181], v[200:203], v[128:131]
	v_mfma_f32_16x16x32_bf16 v[124:127], v[186:189], v[200:203], v[124:127]
	v_mfma_f32_16x16x32_bf16 v[100:103], v[178:181], v[208:211], v[100:103]
	v_mfma_f32_16x16x32_bf16 v[96:99], v[186:189], v[208:211], v[96:99]
	v_mfma_f32_16x16x32_bf16 v[84:87], v[178:181], v[216:219], v[84:87]
	v_mfma_f32_16x16x32_bf16 v[80:83], v[186:189], v[216:219], v[80:83]
	v_mfma_f32_16x16x32_bf16 v[68:71], v[178:181], v[224:227], v[68:71]
	v_mfma_f32_16x16x32_bf16 v[64:67], v[186:189], v[224:227], v[64:67]
	v_mfma_f32_16x16x32_bf16 v[128:131], v[182:185], v[204:207], v[128:131]
	v_mfma_f32_16x16x32_bf16 v[124:127], v[190:193], v[204:207], v[124:127]
	v_mfma_f32_16x16x32_bf16 v[100:103], v[182:185], v[212:215], v[100:103]
	v_mfma_f32_16x16x32_bf16 v[96:99], v[190:193], v[212:215], v[96:99]
	v_mfma_f32_16x16x32_bf16 v[84:87], v[182:185], v[220:223], v[84:87]
	v_mfma_f32_16x16x32_bf16 v[80:83], v[190:193], v[220:223], v[80:83]
	v_mfma_f32_16x16x32_bf16 v[68:71], v[182:185], v[228:231], v[68:71]
	v_mfma_f32_16x16x32_bf16 v[64:67], v[190:193], v[228:231], v[64:67]
	s_setprio 0
	s_barrier
	s_add_i32 s70, s50, s30
	v_lshl_add_u64 v[194:195], s[4:5], 0, v[144:145]
	s_mov_b32 m0, s70
	ds_read_b128 v[200:203], v174 offset:16384
	ds_read_b128 v[204:207], v174 offset:17408
	ds_read_b128 v[208:211], v174 offset:18432
	ds_read_b128 v[212:215], v174 offset:19456
	ds_read_b128 v[216:219], v174 offset:20480
	ds_read_b128 v[220:223], v174 offset:21504
	ds_read_b128 v[224:227], v174 offset:22528
	ds_read_b128 v[228:231], v174 offset:23552
	global_load_lds_dwordx4 v[194:195], off
	s_add_i32 m0, s70, 0x2000
	s_add_u32 s70, s4, 0x18000
	v_lshl_add_u64 v[232:233], s[4:5], 0, v[148:149]
	s_addc_u32 s71, s5, 0
	s_add_i32 s72, s51, s30
	global_load_lds_dwordx4 v[232:233], off
	v_lshl_add_u64 v[234:235], s[70:71], 0, v[144:145]
	s_mov_b32 m0, s72
	v_lshl_add_u64 v[236:237], s[6:7], 0, v[146:147]
	global_load_lds_dwordx4 v[234:235], off
	v_lshl_add_u64 v[234:235], s[70:71], 0, v[148:149]
	s_add_i32 m0, s72, 0x2000
	s_nop 0
	global_load_lds_dwordx4 v[234:235], off
	v_lshl_add_u64 v[234:235], s[6:7], 0, v[142:143]
	s_mov_b32 m0, s31
	s_nop 0
	global_load_lds_dwordx4 v[234:235], off
	s_mov_b32 m0, s33
	s_nop 0
	global_load_lds_dwordx4 v[236:237], off
	s_waitcnt vmcnt(8)
	s_waitcnt lgkmcnt(0)
	s_barrier
	s_setprio 1
	v_mfma_f32_16x16x32_bf16 v[60:63], v[104:107], v[200:203], v[60:63]
	v_mfma_f32_16x16x32_bf16 v[56:59], v[112:115], v[200:203], v[56:59]
	v_mfma_f32_16x16x32_bf16 v[44:47], v[104:107], v[208:211], v[44:47]
	v_mfma_f32_16x16x32_bf16 v[40:43], v[112:115], v[208:211], v[40:43]
	v_mfma_f32_16x16x32_bf16 v[28:31], v[104:107], v[216:219], v[28:31]
	v_mfma_f32_16x16x32_bf16 v[24:27], v[112:115], v[216:219], v[24:27]
	v_mfma_f32_16x16x32_bf16 v[12:15], v[104:107], v[224:227], v[12:15]
	v_mfma_f32_16x16x32_bf16 v[8:11], v[112:115], v[224:227], v[8:11]
	v_mfma_f32_16x16x32_bf16 v[60:63], v[108:111], v[204:207], v[60:63]
	v_mfma_f32_16x16x32_bf16 v[56:59], v[158:161], v[204:207], v[56:59]
	v_mfma_f32_16x16x32_bf16 v[44:47], v[108:111], v[212:215], v[44:47]
	v_mfma_f32_16x16x32_bf16 v[40:43], v[158:161], v[212:215], v[40:43]
	v_mfma_f32_16x16x32_bf16 v[28:31], v[108:111], v[220:223], v[28:31]
	v_mfma_f32_16x16x32_bf16 v[24:27], v[158:161], v[220:223], v[24:27]
	v_mfma_f32_16x16x32_bf16 v[12:15], v[108:111], v[228:231], v[12:15]
	v_mfma_f32_16x16x32_bf16 v[8:11], v[158:161], v[228:231], v[8:11]
	s_setprio 0
	s_setprio 1
	v_mfma_f32_16x16x32_bf16 v[52:55], v[178:181], v[200:203], v[52:55]
	v_mfma_f32_16x16x32_bf16 v[48:51], v[186:189], v[200:203], v[48:51]
	v_mfma_f32_16x16x32_bf16 v[36:39], v[178:181], v[208:211], v[36:39]
	v_mfma_f32_16x16x32_bf16 v[32:35], v[186:189], v[208:211], v[32:35]
	v_mfma_f32_16x16x32_bf16 v[20:23], v[178:181], v[216:219], v[20:23]
	v_mfma_f32_16x16x32_bf16 v[16:19], v[186:189], v[216:219], v[16:19]
	v_mfma_f32_16x16x32_bf16 v[4:7], v[178:181], v[224:227], v[4:7]
	v_mfma_f32_16x16x32_bf16 v[0:3], v[186:189], v[224:227], v[0:3]
	v_mfma_f32_16x16x32_bf16 v[52:55], v[182:185], v[204:207], v[52:55]
	v_mfma_f32_16x16x32_bf16 v[48:51], v[190:193], v[204:207], v[48:51]
	v_mfma_f32_16x16x32_bf16 v[36:39], v[182:185], v[212:215], v[36:39]
	v_mfma_f32_16x16x32_bf16 v[32:35], v[190:193], v[212:215], v[32:35]
	v_mfma_f32_16x16x32_bf16 v[20:23], v[182:185], v[220:223], v[20:23]
	v_mfma_f32_16x16x32_bf16 v[16:19], v[190:193], v[220:223], v[16:19]
	v_mfma_f32_16x16x32_bf16 v[4:7], v[182:185], v[228:231], v[4:7]
	v_mfma_f32_16x16x32_bf16 v[0:3], v[190:193], v[228:231], v[0:3]
	s_setprio 0
	s_barrier
	s_add_i32 s70, 0, 0x18000
	v_add_u32_e32 v150, s70, v170
	s_add_i32 s71, 0, 0x1c000
	ds_read_b128 v[104:107], v150
	ds_read_b128 v[108:111], v150 offset:1024
	ds_read_b128 v[112:115], v150 offset:2048
	ds_read_b128 v[158:161], v150 offset:3072
	v_add_u32_e32 v150, s71, v170
	ds_read_b128 v[178:181], v150
	ds_read_b128 v[182:185], v150 offset:1024
	ds_read_b128 v[186:189], v150 offset:2048
	ds_read_b128 v[190:193], v150 offset:3072
	s_add_u32 s6, s6, 0x90000
	s_addc_u32 s7, s7, 0
	s_mov_b32 m0, s42
	v_lshl_add_u64 v[238:239], s[6:7], 0, v[142:143]
	ds_read_b128 v[200:203], v174 offset:32768
	ds_read_b128 v[204:207], v174 offset:33792
	ds_read_b128 v[208:211], v174 offset:34816
	ds_read_b128 v[212:215], v174 offset:35840
	ds_read_b128 v[216:219], v174 offset:36864
	ds_read_b128 v[220:223], v174 offset:37888
	ds_read_b128 v[224:227], v174 offset:38912
	ds_read_b128 v[228:231], v174 offset:39936
	global_load_lds_dwordx4 v[238:239], off
	v_lshl_add_u64 v[238:239], s[6:7], 0, v[146:147]
	s_mov_b32 m0, s43
	s_nop 0
	global_load_lds_dwordx4 v[238:239], off
	s_waitcnt vmcnt(8)
	s_waitcnt lgkmcnt(0)
	s_barrier
	s_setprio 1
	v_mfma_f32_16x16x32_bf16 v[136:139], v[104:107], v[200:203], v[136:139]
	v_mfma_f32_16x16x32_bf16 v[132:135], v[112:115], v[200:203], v[132:135]
	v_mfma_f32_16x16x32_bf16 v[120:123], v[104:107], v[208:211], v[120:123]
	v_mfma_f32_16x16x32_bf16 v[116:119], v[112:115], v[208:211], v[116:119]
	v_mfma_f32_16x16x32_bf16 v[92:95], v[104:107], v[216:219], v[92:95]
	v_mfma_f32_16x16x32_bf16 v[88:91], v[112:115], v[216:219], v[88:91]
	v_mfma_f32_16x16x32_bf16 v[76:79], v[104:107], v[224:227], v[76:79]
	v_mfma_f32_16x16x32_bf16 v[72:75], v[112:115], v[224:227], v[72:75]
	v_mfma_f32_16x16x32_bf16 v[136:139], v[108:111], v[204:207], v[136:139]
	v_mfma_f32_16x16x32_bf16 v[132:135], v[158:161], v[204:207], v[132:135]
	v_mfma_f32_16x16x32_bf16 v[120:123], v[108:111], v[212:215], v[120:123]
	v_mfma_f32_16x16x32_bf16 v[116:119], v[158:161], v[212:215], v[116:119]
	v_mfma_f32_16x16x32_bf16 v[92:95], v[108:111], v[220:223], v[92:95]
	v_mfma_f32_16x16x32_bf16 v[88:91], v[158:161], v[220:223], v[88:91]
	v_mfma_f32_16x16x32_bf16 v[76:79], v[108:111], v[228:231], v[76:79]
	v_mfma_f32_16x16x32_bf16 v[72:75], v[158:161], v[228:231], v[72:75]
	s_setprio 0
	s_setprio 1
	v_mfma_f32_16x16x32_bf16 v[128:131], v[178:181], v[200:203], v[128:131]
	v_mfma_f32_16x16x32_bf16 v[124:127], v[186:189], v[200:203], v[124:127]
	v_mfma_f32_16x16x32_bf16 v[100:103], v[178:181], v[208:211], v[100:103]
	v_mfma_f32_16x16x32_bf16 v[96:99], v[186:189], v[208:211], v[96:99]
	v_mfma_f32_16x16x32_bf16 v[84:87], v[178:181], v[216:219], v[84:87]
	v_mfma_f32_16x16x32_bf16 v[80:83], v[186:189], v[216:219], v[80:83]
	v_mfma_f32_16x16x32_bf16 v[68:71], v[178:181], v[224:227], v[68:71]
	v_mfma_f32_16x16x32_bf16 v[64:67], v[186:189], v[224:227], v[64:67]
	v_mfma_f32_16x16x32_bf16 v[128:131], v[182:185], v[204:207], v[128:131]
	v_mfma_f32_16x16x32_bf16 v[124:127], v[190:193], v[204:207], v[124:127]
	v_mfma_f32_16x16x32_bf16 v[100:103], v[182:185], v[212:215], v[100:103]
	v_mfma_f32_16x16x32_bf16 v[96:99], v[190:193], v[212:215], v[96:99]
	v_mfma_f32_16x16x32_bf16 v[84:87], v[182:185], v[220:223], v[84:87]
	v_mfma_f32_16x16x32_bf16 v[80:83], v[190:193], v[220:223], v[80:83]
	v_mfma_f32_16x16x32_bf16 v[68:71], v[182:185], v[228:231], v[68:71]
	v_mfma_f32_16x16x32_bf16 v[64:67], v[190:193], v[228:231], v[64:67]
	s_setprio 0
	s_barrier
	s_add_i32 s6, s70, s30
	v_lshl_add_u64 v[194:195], v[194:195], 0, s[10:11]
	s_mov_b32 m0, s6
	ds_read_b128 v[200:203], v174 offset:49152
	ds_read_b128 v[204:207], v174 offset:50176
	ds_read_b128 v[208:211], v174 offset:51200
	ds_read_b128 v[212:215], v174 offset:52224
	ds_read_b128 v[216:219], v174 offset:53248
	ds_read_b128 v[220:223], v174 offset:54272
	ds_read_b128 v[224:227], v174 offset:55296
	ds_read_b128 v[228:231], v174 offset:56320
	global_load_lds_dwordx4 v[194:195], off
	s_add_i32 m0, s6, 0x2000
	s_add_u32 s4, s4, 0x18080
	v_lshl_add_u64 v[194:195], v[232:233], 0, s[10:11]
	s_addc_u32 s5, s5, 0
	s_add_i32 s6, s71, s30
	global_load_lds_dwordx4 v[194:195], off
	v_lshl_add_u64 v[194:195], s[4:5], 0, v[144:145]
	s_mov_b32 m0, s6
	s_nop 0
	global_load_lds_dwordx4 v[194:195], off
	v_lshl_add_u64 v[194:195], s[4:5], 0, v[148:149]
	s_add_i32 m0, s6, 0x2000
	s_nop 0
	global_load_lds_dwordx4 v[194:195], off
	v_lshl_add_u64 v[194:195], v[234:235], 0, s[10:11]
	s_mov_b32 m0, s45
	s_nop 0
	global_load_lds_dwordx4 v[194:195], off
	v_lshl_add_u64 v[194:195], v[236:237], 0, s[10:11]
	s_mov_b32 m0, s46
	s_nop 0
	global_load_lds_dwordx4 v[194:195], off
	s_waitcnt vmcnt(8)
	s_waitcnt lgkmcnt(0)
	s_barrier
	s_setprio 1
	v_mfma_f32_16x16x32_bf16 v[60:63], v[104:107], v[200:203], v[60:63]
	v_mfma_f32_16x16x32_bf16 v[56:59], v[112:115], v[200:203], v[56:59]
	v_mfma_f32_16x16x32_bf16 v[44:47], v[104:107], v[208:211], v[44:47]
	v_mfma_f32_16x16x32_bf16 v[40:43], v[112:115], v[208:211], v[40:43]
	v_mfma_f32_16x16x32_bf16 v[28:31], v[104:107], v[216:219], v[28:31]
	v_mfma_f32_16x16x32_bf16 v[24:27], v[112:115], v[216:219], v[24:27]
	v_mfma_f32_16x16x32_bf16 v[12:15], v[104:107], v[224:227], v[12:15]
	v_mfma_f32_16x16x32_bf16 v[8:11], v[112:115], v[224:227], v[8:11]
	v_mfma_f32_16x16x32_bf16 v[60:63], v[108:111], v[204:207], v[60:63]
	v_mfma_f32_16x16x32_bf16 v[56:59], v[158:161], v[204:207], v[56:59]
	v_mfma_f32_16x16x32_bf16 v[44:47], v[108:111], v[212:215], v[44:47]
	v_mfma_f32_16x16x32_bf16 v[40:43], v[158:161], v[212:215], v[40:43]
	v_mfma_f32_16x16x32_bf16 v[28:31], v[108:111], v[220:223], v[28:31]
	v_mfma_f32_16x16x32_bf16 v[24:27], v[158:161], v[220:223], v[24:27]
	v_mfma_f32_16x16x32_bf16 v[12:15], v[108:111], v[228:231], v[12:15]
	v_mfma_f32_16x16x32_bf16 v[8:11], v[158:161], v[228:231], v[8:11]
	s_setprio 0
	s_setprio 1
	v_mfma_f32_16x16x32_bf16 v[52:55], v[178:181], v[200:203], v[52:55]
	v_mfma_f32_16x16x32_bf16 v[48:51], v[186:189], v[200:203], v[48:51]
	v_mfma_f32_16x16x32_bf16 v[36:39], v[178:181], v[208:211], v[36:39]
	v_mfma_f32_16x16x32_bf16 v[32:35], v[186:189], v[208:211], v[32:35]
	v_mfma_f32_16x16x32_bf16 v[20:23], v[178:181], v[216:219], v[20:23]
	v_mfma_f32_16x16x32_bf16 v[16:19], v[186:189], v[216:219], v[16:19]
	v_mfma_f32_16x16x32_bf16 v[4:7], v[178:181], v[224:227], v[4:7]
	v_mfma_f32_16x16x32_bf16 v[0:3], v[186:189], v[224:227], v[0:3]
	v_mfma_f32_16x16x32_bf16 v[52:55], v[182:185], v[204:207], v[52:55]
	v_mfma_f32_16x16x32_bf16 v[48:51], v[190:193], v[204:207], v[48:51]
	v_mfma_f32_16x16x32_bf16 v[36:39], v[182:185], v[212:215], v[36:39]
	v_mfma_f32_16x16x32_bf16 v[32:35], v[190:193], v[212:215], v[32:35]
	v_mfma_f32_16x16x32_bf16 v[20:23], v[182:185], v[220:223], v[20:23]
	v_mfma_f32_16x16x32_bf16 v[16:19], v[190:193], v[220:223], v[16:19]
	v_mfma_f32_16x16x32_bf16 v[4:7], v[182:185], v[228:231], v[4:7]
	v_mfma_f32_16x16x32_bf16 v[0:3], v[190:193], v[228:231], v[0:3]
	s_setprio 0
	s_barrier
	s_add_i32 s69, s69, 2
	s_add_u32 s0, s0, 0x100
	s_addc_u32 s1, s1, 0
	s_add_u32 s67, s67, 0x100
	s_addc_u32 s68, s68, 0
	s_cmp_gt_u32 s69, 3
	s_cbranch_scc0 .LBB0_424
	s_and_b64 vcc, exec, s[12:13]
	s_cbranch_vccz .LBB0_427
	s_barrier

.LBB0_486:
	s_add_u32 s48, s26, s42
	s_addc_u32 s49, s27, s43
	s_add_u32 s46, s48, 0x100
	s_addc_u32 s47, s49, 0
	s_and_b64 s[44:45], s[30:31], exec
	s_cselect_b32 s45, s21, s47
	s_cselect_b32 s44, s20, s46
	s_add_u32 s42, s0, s42
	s_addc_u32 s43, s1, s43
	s_add_u32 s42, s42, 0x100
	s_addc_u32 s43, s43, 0
	s_and_b64 s[30:31], s[30:31], exec
	s_cselect_b32 s47, s19, s43
	s_cselect_b32 s46, s70, s42
	s_add_u32 s50, s48, 0x90080
	ds_read_b128 v[150:153], v144
	ds_read_b128 v[154:157], v144 offset:1024
	ds_read_b128 v[158:161], v144 offset:2048
	ds_read_b128 v[164:167], v144 offset:3072
	ds_read_b128 v[168:171], v145
	ds_read_b128 v[172:175], v145 offset:1024
	ds_read_b128 v[176:179], v145 offset:2048
	ds_read_b128 v[180:183], v145 offset:3072
	s_addc_u32 s51, s49, 0
	s_add_i32 s80, s63, s53
	s_add_i32 m0, s25, 0xc000
	s_add_i32 s81, s25, 0xe000
	s_add_i32 s77, s80, 0x2000
	s_add_u32 s48, s46, 0x10000
	s_addc_u32 s49, s47, 0
	s_add_i32 s79, s64, s53
	s_add_i32 s78, s79, 0x2000
	s_add_i32 s76, 0, 0x18000
	s_add_i32 s75, 0, 0x1c000
	s_add_u32 s42, s44, 0x90000
	s_addc_u32 s43, s45, 0
	s_add_i32 s74, s76, s53
	s_add_i32 s72, s74, 0x2000
	s_add_u32 s30, s46, 0x10080
	s_addc_u32 s31, s47, 0
	s_add_i32 s73, s75, s53
	s_add_i32 s71, s73, 0x2000
	v_lshl_add_u64 v[140:141], s[50:51], 0, v[128:129]
	ds_read_b128 v[184:187], v146
	ds_read_b128 v[188:191], v146 offset:1024
	ds_read_b128 v[192:195], v146 offset:2048
	ds_read_b128 v[200:203], v146 offset:3072
	ds_read_b128 v[204:207], v146 offset:4096
	ds_read_b128 v[208:211], v146 offset:5120
	ds_read_b128 v[212:215], v146 offset:6144
	ds_read_b128 v[216:219], v146 offset:7168
	global_load_lds_dwordx4 v[140:141], off
	v_lshl_add_u64 v[140:141], s[50:51], 0, v[132:133]
	s_mov_b32 m0, s81
	s_nop 0
	global_load_lds_dwordx4 v[140:141], off
	s_waitcnt vmcnt(8)
	s_waitcnt lgkmcnt(0)
	s_barrier
	s_setprio 1
	v_mfma_f32_16x16x32_bf16 v[124:127], v[150:153], v[184:187], v[124:127]
	v_mfma_f32_16x16x32_bf16 v[120:123], v[158:161], v[184:187], v[120:123]
	v_mfma_f32_16x16x32_bf16 v[108:111], v[150:153], v[192:195], v[108:111]
	v_mfma_f32_16x16x32_bf16 v[104:107], v[158:161], v[192:195], v[104:107]
	v_mfma_f32_16x16x32_bf16 v[92:95], v[150:153], v[204:207], v[92:95]
	v_mfma_f32_16x16x32_bf16 v[88:91], v[158:161], v[204:207], v[88:91]
	v_mfma_f32_16x16x32_bf16 v[76:79], v[150:153], v[212:215], v[76:79]
	v_mfma_f32_16x16x32_bf16 v[72:75], v[158:161], v[212:215], v[72:75]
	v_mfma_f32_16x16x32_bf16 v[124:127], v[154:157], v[188:191], v[124:127]
	v_mfma_f32_16x16x32_bf16 v[120:123], v[164:167], v[188:191], v[120:123]
	v_mfma_f32_16x16x32_bf16 v[108:111], v[154:157], v[200:203], v[108:111]
	v_mfma_f32_16x16x32_bf16 v[104:107], v[164:167], v[200:203], v[104:107]
	v_mfma_f32_16x16x32_bf16 v[92:95], v[154:157], v[208:211], v[92:95]
	v_mfma_f32_16x16x32_bf16 v[88:91], v[164:167], v[208:211], v[88:91]
	v_mfma_f32_16x16x32_bf16 v[76:79], v[154:157], v[216:219], v[76:79]
	v_mfma_f32_16x16x32_bf16 v[72:75], v[164:167], v[216:219], v[72:75]
	s_setprio 0
	s_setprio 1
	v_mfma_f32_16x16x32_bf16 v[116:119], v[168:171], v[184:187], v[116:119]
	v_mfma_f32_16x16x32_bf16 v[112:115], v[176:179], v[184:187], v[112:115]
	v_mfma_f32_16x16x32_bf16 v[100:103], v[168:171], v[192:195], v[100:103]
	v_mfma_f32_16x16x32_bf16 v[96:99], v[176:179], v[192:195], v[96:99]
	v_mfma_f32_16x16x32_bf16 v[84:87], v[168:171], v[204:207], v[84:87]
	v_mfma_f32_16x16x32_bf16 v[80:83], v[176:179], v[204:207], v[80:83]
	v_mfma_f32_16x16x32_bf16 v[68:71], v[168:171], v[212:215], v[68:71]
	v_mfma_f32_16x16x32_bf16 v[64:67], v[176:179], v[212:215], v[64:67]
	v_mfma_f32_16x16x32_bf16 v[116:119], v[172:175], v[188:191], v[116:119]
	v_mfma_f32_16x16x32_bf16 v[112:115], v[180:183], v[188:191], v[112:115]
	v_mfma_f32_16x16x32_bf16 v[100:103], v[172:175], v[200:203], v[100:103]
	v_mfma_f32_16x16x32_bf16 v[96:99], v[180:183], v[200:203], v[96:99]
	v_mfma_f32_16x16x32_bf16 v[84:87], v[172:175], v[208:211], v[84:87]
	v_mfma_f32_16x16x32_bf16 v[80:83], v[180:183], v[208:211], v[80:83]
	v_mfma_f32_16x16x32_bf16 v[68:71], v[172:175], v[216:219], v[68:71]
	v_mfma_f32_16x16x32_bf16 v[64:67], v[180:183], v[216:219], v[64:67]
	s_setprio 0
	s_barrier
	s_mov_b32 m0, s80
	v_lshl_add_u64 v[140:141], s[46:47], 0, v[130:131]
	ds_read_b128 v[184:187], v146 offset:16384
	ds_read_b128 v[188:191], v146 offset:17408
	ds_read_b128 v[192:195], v146 offset:18432
	ds_read_b128 v[200:203], v146 offset:19456
	ds_read_b128 v[204:207], v146 offset:20480
	ds_read_b128 v[208:211], v146 offset:21504
	ds_read_b128 v[212:215], v146 offset:22528
	ds_read_b128 v[216:219], v146 offset:23552
	global_load_lds_dwordx4 v[140:141], off
	v_lshl_add_u64 v[220:221], s[46:47], 0, v[134:135]
	s_mov_b32 m0, s77
	v_lshl_add_u64 v[222:223], s[48:49], 0, v[130:131]
	global_load_lds_dwordx4 v[220:221], off
	s_mov_b32 m0, s79
	v_lshl_add_u64 v[224:225], s[44:45], 0, v[132:133]
	global_load_lds_dwordx4 v[222:223], off
	v_lshl_add_u64 v[222:223], s[48:49], 0, v[134:135]
	s_mov_b32 m0, s78
	s_nop 0
	global_load_lds_dwordx4 v[222:223], off
	v_lshl_add_u64 v[222:223], s[44:45], 0, v[128:129]
	s_mov_b32 m0, s25
	s_nop 0
	global_load_lds_dwordx4 v[222:223], off
	s_mov_b32 m0, s56
	s_nop 0
	global_load_lds_dwordx4 v[224:225], off
	s_waitcnt vmcnt(8)
	s_waitcnt lgkmcnt(0)
	s_barrier
	s_setprio 1
	v_mfma_f32_16x16x32_bf16 v[60:63], v[150:153], v[184:187], v[60:63]
	v_mfma_f32_16x16x32_bf16 v[56:59], v[158:161], v[184:187], v[56:59]
	v_mfma_f32_16x16x32_bf16 v[44:47], v[150:153], v[192:195], v[44:47]
	v_mfma_f32_16x16x32_bf16 v[40:43], v[158:161], v[192:195], v[40:43]
	v_mfma_f32_16x16x32_bf16 v[28:31], v[150:153], v[204:207], v[28:31]
	v_mfma_f32_16x16x32_bf16 v[24:27], v[158:161], v[204:207], v[24:27]
	v_mfma_f32_16x16x32_bf16 v[12:15], v[150:153], v[212:215], v[12:15]
	v_mfma_f32_16x16x32_bf16 v[8:11], v[158:161], v[212:215], v[8:11]
	v_mfma_f32_16x16x32_bf16 v[60:63], v[154:157], v[188:191], v[60:63]
	v_mfma_f32_16x16x32_bf16 v[56:59], v[164:167], v[188:191], v[56:59]
	v_mfma_f32_16x16x32_bf16 v[44:47], v[154:157], v[200:203], v[44:47]
	v_mfma_f32_16x16x32_bf16 v[40:43], v[164:167], v[200:203], v[40:43]
	v_mfma_f32_16x16x32_bf16 v[28:31], v[154:157], v[208:211], v[28:31]
	v_mfma_f32_16x16x32_bf16 v[24:27], v[164:167], v[208:211], v[24:27]
	v_mfma_f32_16x16x32_bf16 v[12:15], v[154:157], v[216:219], v[12:15]
	v_mfma_f32_16x16x32_bf16 v[8:11], v[164:167], v[216:219], v[8:11]
	s_setprio 0
	s_setprio 1
	v_mfma_f32_16x16x32_bf16 v[52:55], v[168:171], v[184:187], v[52:55]
	v_mfma_f32_16x16x32_bf16 v[48:51], v[176:179], v[184:187], v[48:51]
	v_mfma_f32_16x16x32_bf16 v[36:39], v[168:171], v[192:195], v[36:39]
	v_mfma_f32_16x16x32_bf16 v[32:35], v[176:179], v[192:195], v[32:35]
	v_mfma_f32_16x16x32_bf16 v[20:23], v[168:171], v[204:207], v[20:23]
	v_mfma_f32_16x16x32_bf16 v[16:19], v[176:179], v[204:207], v[16:19]
	v_mfma_f32_16x16x32_bf16 v[4:7], v[168:171], v[212:215], v[4:7]
	v_mfma_f32_16x16x32_bf16 v[0:3], v[176:179], v[212:215], v[0:3]
	v_mfma_f32_16x16x32_bf16 v[52:55], v[172:175], v[188:191], v[52:55]
	v_mfma_f32_16x16x32_bf16 v[48:51], v[180:183], v[188:191], v[48:51]
	v_mfma_f32_16x16x32_bf16 v[36:39], v[172:175], v[200:203], v[36:39]
	v_mfma_f32_16x16x32_bf16 v[32:35], v[180:183], v[200:203], v[32:35]
	v_mfma_f32_16x16x32_bf16 v[20:23], v[172:175], v[208:211], v[20:23]
	v_mfma_f32_16x16x32_bf16 v[16:19], v[180:183], v[208:211], v[16:19]
	v_mfma_f32_16x16x32_bf16 v[4:7], v[172:175], v[216:219], v[4:7]
	v_mfma_f32_16x16x32_bf16 v[0:3], v[180:183], v[216:219], v[0:3]
	s_setprio 0
	s_barrier
	v_add_u32_e32 v142, s76, v143
	ds_read_b128 v[150:153], v142
	ds_read_b128 v[154:157], v142 offset:1024
	ds_read_b128 v[158:161], v142 offset:2048
	ds_read_b128 v[164:167], v142 offset:3072
	v_add_u32_e32 v142, s75, v143
	ds_read_b128 v[168:171], v142
	ds_read_b128 v[172:175], v142 offset:1024
	ds_read_b128 v[176:179], v142 offset:2048
	ds_read_b128 v[180:183], v142 offset:3072
	s_mov_b32 m0, s57
	v_lshl_add_u64 v[226:227], s[42:43], 0, v[128:129]
	ds_read_b128 v[184:187], v146 offset:32768
	ds_read_b128 v[188:191], v146 offset:33792
	ds_read_b128 v[192:195], v146 offset:34816
	ds_read_b128 v[200:203], v146 offset:35840
	ds_read_b128 v[204:207], v146 offset:36864
	ds_read_b128 v[208:211], v146 offset:37888
	ds_read_b128 v[212:215], v146 offset:38912
	ds_read_b128 v[216:219], v146 offset:39936
	global_load_lds_dwordx4 v[226:227], off
	v_lshl_add_u64 v[226:227], s[42:43], 0, v[132:133]
	s_mov_b32 m0, s58
	s_nop 0
	global_load_lds_dwordx4 v[226:227], off
	s_waitcnt vmcnt(8)
	s_waitcnt lgkmcnt(0)
	s_barrier
	s_setprio 1
	v_mfma_f32_16x16x32_bf16 v[124:127], v[150:153], v[184:187], v[124:127]
	v_mfma_f32_16x16x32_bf16 v[120:123], v[158:161], v[184:187], v[120:123]
	v_mfma_f32_16x16x32_bf16 v[108:111], v[150:153], v[192:195], v[108:111]
	v_mfma_f32_16x16x32_bf16 v[104:107], v[158:161], v[192:195], v[104:107]
	v_mfma_f32_16x16x32_bf16 v[92:95], v[150:153], v[204:207], v[92:95]
	v_mfma_f32_16x16x32_bf16 v[88:91], v[158:161], v[204:207], v[88:91]
	v_mfma_f32_16x16x32_bf16 v[76:79], v[150:153], v[212:215], v[76:79]
	v_mfma_f32_16x16x32_bf16 v[72:75], v[158:161], v[212:215], v[72:75]
	v_mfma_f32_16x16x32_bf16 v[124:127], v[154:157], v[188:191], v[124:127]
	v_mfma_f32_16x16x32_bf16 v[120:123], v[164:167], v[188:191], v[120:123]
	v_mfma_f32_16x16x32_bf16 v[108:111], v[154:157], v[200:203], v[108:111]
	v_mfma_f32_16x16x32_bf16 v[104:107], v[164:167], v[200:203], v[104:107]
	v_mfma_f32_16x16x32_bf16 v[92:95], v[154:157], v[208:211], v[92:95]
	v_mfma_f32_16x16x32_bf16 v[88:91], v[164:167], v[208:211], v[88:91]
	v_mfma_f32_16x16x32_bf16 v[76:79], v[154:157], v[216:219], v[76:79]
	v_mfma_f32_16x16x32_bf16 v[72:75], v[164:167], v[216:219], v[72:75]
	s_setprio 0
	s_setprio 1
	v_mfma_f32_16x16x32_bf16 v[116:119], v[168:171], v[184:187], v[116:119]
	v_mfma_f32_16x16x32_bf16 v[112:115], v[176:179], v[184:187], v[112:115]
	v_mfma_f32_16x16x32_bf16 v[100:103], v[168:171], v[192:195], v[100:103]
	v_mfma_f32_16x16x32_bf16 v[96:99], v[176:179], v[192:195], v[96:99]
	v_mfma_f32_16x16x32_bf16 v[84:87], v[168:171], v[204:207], v[84:87]
	v_mfma_f32_16x16x32_bf16 v[80:83], v[176:179], v[204:207], v[80:83]
	v_mfma_f32_16x16x32_bf16 v[68:71], v[168:171], v[212:215], v[68:71]
	v_mfma_f32_16x16x32_bf16 v[64:67], v[176:179], v[212:215], v[64:67]
	v_mfma_f32_16x16x32_bf16 v[116:119], v[172:175], v[188:191], v[116:119]
	v_mfma_f32_16x16x32_bf16 v[112:115], v[180:183], v[188:191], v[112:115]
	v_mfma_f32_16x16x32_bf16 v[100:103], v[172:175], v[200:203], v[100:103]
	v_mfma_f32_16x16x32_bf16 v[96:99], v[180:183], v[200:203], v[96:99]
	v_mfma_f32_16x16x32_bf16 v[84:87], v[172:175], v[208:211], v[84:87]
	v_mfma_f32_16x16x32_bf16 v[80:83], v[180:183], v[208:211], v[80:83]
	v_mfma_f32_16x16x32_bf16 v[68:71], v[172:175], v[216:219], v[68:71]
	v_mfma_f32_16x16x32_bf16 v[64:67], v[180:183], v[216:219], v[64:67]
	s_setprio 0
	s_barrier
	s_mov_b32 m0, s74
	v_lshl_add_u64 v[140:141], v[140:141], 0, s[8:9]
	ds_read_b128 v[184:187], v146 offset:49152
	ds_read_b128 v[188:191], v146 offset:50176
	ds_read_b128 v[192:195], v146 offset:51200
	ds_read_b128 v[200:203], v146 offset:52224
	ds_read_b128 v[204:207], v146 offset:53248
	ds_read_b128 v[208:211], v146 offset:54272
	ds_read_b128 v[212:215], v146 offset:55296
	ds_read_b128 v[216:219], v146 offset:56320
	global_load_lds_dwordx4 v[140:141], off
	v_lshl_add_u64 v[140:141], v[220:221], 0, s[8:9]
	s_mov_b32 m0, s72
	s_nop 0
	global_load_lds_dwordx4 v[140:141], off
	v_lshl_add_u64 v[140:141], s[30:31], 0, v[130:131]
	s_mov_b32 m0, s73
	s_nop 0
	global_load_lds_dwordx4 v[140:141], off
	v_lshl_add_u64 v[140:141], s[30:31], 0, v[134:135]
	s_mov_b32 m0, s71
	s_nop 0
	global_load_lds_dwordx4 v[140:141], off
	v_lshl_add_u64 v[140:141], v[222:223], 0, s[8:9]
	s_mov_b32 m0, s60
	s_nop 0
	global_load_lds_dwordx4 v[140:141], off
	v_lshl_add_u64 v[140:141], v[224:225], 0, s[8:9]
	s_mov_b32 m0, s61
	s_nop 0
	global_load_lds_dwordx4 v[140:141], off
	s_waitcnt vmcnt(8)
	s_waitcnt lgkmcnt(0)
	s_barrier
	s_setprio 1
	v_mfma_f32_16x16x32_bf16 v[60:63], v[150:153], v[184:187], v[60:63]
	v_mfma_f32_16x16x32_bf16 v[56:59], v[158:161], v[184:187], v[56:59]
	v_mfma_f32_16x16x32_bf16 v[44:47], v[150:153], v[192:195], v[44:47]
	v_mfma_f32_16x16x32_bf16 v[40:43], v[158:161], v[192:195], v[40:43]
	v_mfma_f32_16x16x32_bf16 v[28:31], v[150:153], v[204:207], v[28:31]
	v_mfma_f32_16x16x32_bf16 v[24:27], v[158:161], v[204:207], v[24:27]
	v_mfma_f32_16x16x32_bf16 v[12:15], v[150:153], v[212:215], v[12:15]
	v_mfma_f32_16x16x32_bf16 v[8:11], v[158:161], v[212:215], v[8:11]
	v_mfma_f32_16x16x32_bf16 v[60:63], v[154:157], v[188:191], v[60:63]
	v_mfma_f32_16x16x32_bf16 v[56:59], v[164:167], v[188:191], v[56:59]
	v_mfma_f32_16x16x32_bf16 v[44:47], v[154:157], v[200:203], v[44:47]
	v_mfma_f32_16x16x32_bf16 v[40:43], v[164:167], v[200:203], v[40:43]
	v_mfma_f32_16x16x32_bf16 v[28:31], v[154:157], v[208:211], v[28:31]
	v_mfma_f32_16x16x32_bf16 v[24:27], v[164:167], v[208:211], v[24:27]
	v_mfma_f32_16x16x32_bf16 v[12:15], v[154:157], v[216:219], v[12:15]
	v_mfma_f32_16x16x32_bf16 v[8:11], v[164:167], v[216:219], v[8:11]
	s_setprio 0
	s_setprio 1
	v_mfma_f32_16x16x32_bf16 v[52:55], v[168:171], v[184:187], v[52:55]
	v_mfma_f32_16x16x32_bf16 v[48:51], v[176:179], v[184:187], v[48:51]
	v_mfma_f32_16x16x32_bf16 v[36:39], v[168:171], v[192:195], v[36:39]
	v_mfma_f32_16x16x32_bf16 v[32:35], v[176:179], v[192:195], v[32:35]
	v_mfma_f32_16x16x32_bf16 v[20:23], v[168:171], v[204:207], v[20:23]
	v_mfma_f32_16x16x32_bf16 v[16:19], v[176:179], v[204:207], v[16:19]
	v_mfma_f32_16x16x32_bf16 v[4:7], v[168:171], v[212:215], v[4:7]
	v_mfma_f32_16x16x32_bf16 v[0:3], v[176:179], v[212:215], v[0:3]
	v_mfma_f32_16x16x32_bf16 v[52:55], v[172:175], v[188:191], v[52:55]
	v_mfma_f32_16x16x32_bf16 v[48:51], v[180:183], v[188:191], v[48:51]
	v_mfma_f32_16x16x32_bf16 v[36:39], v[172:175], v[200:203], v[36:39]
	v_mfma_f32_16x16x32_bf16 v[32:35], v[180:183], v[200:203], v[32:35]
	v_mfma_f32_16x16x32_bf16 v[20:23], v[172:175], v[208:211], v[20:23]
	v_mfma_f32_16x16x32_bf16 v[16:19], v[180:183], v[208:211], v[16:19]
	v_mfma_f32_16x16x32_bf16 v[4:7], v[172:175], v[216:219], v[4:7]
	v_mfma_f32_16x16x32_bf16 v[0:3], v[180:183], v[216:219], v[0:3]
	s_setprio 0
	s_barrier
	s_andn2_b64 vcc, exec, s[28:29]
	s_mov_b64 s[30:31], -1
	s_mov_b64 s[28:29], 0
	s_mov_b64 s[42:43], 0x100
	s_cbranch_vccz .LBB0_486
	s_and_b64 vcc, exec, s[10:11]
	s_cbranch_vccz .LBB0_489
	s_barrier

.LBB0_730:
	ds_read_b128 v[128:131], v180
	ds_read_b128 v[132:135], v180 offset:1024
	ds_read_b128 v[164:167], v180 offset:2048
	ds_read_b128 v[168:171], v180 offset:3072
	ds_read_b128 v[172:175], v181
	ds_read_b128 v[186:189], v181 offset:1024
	ds_read_b128 v[190:193], v181 offset:2048
	ds_read_b128 v[200:203], v181 offset:3072
	s_add_u32 s4, s0, 0xfffc0080
	s_addc_u32 s5, s1, -1
	s_cmp_eq_u32 s63, 12
	s_cselect_b32 s43, s13, s5
	s_cselect_b32 s42, s37, s4
	s_cselect_b32 s5, s35, s62
	s_cselect_b32 s4, s60, s61
	v_lshl_add_u64 v[194:195], s[0:1], 0, v[156:157]
	s_add_i32 m0, s7, 0xc000
	ds_read_b128 v[204:207], v182
	ds_read_b128 v[208:211], v182 offset:1024
	ds_read_b128 v[212:215], v182 offset:2048
	ds_read_b128 v[216:219], v182 offset:3072
	ds_read_b128 v[220:223], v182 offset:4096
	ds_read_b128 v[224:227], v182 offset:5120
	ds_read_b128 v[228:231], v182 offset:6144
	ds_read_b128 v[232:235], v182 offset:7168
	global_load_lds_dwordx4 v[194:195], off
	v_lshl_add_u64 v[194:195], s[0:1], 0, v[158:159]
	s_add_i32 m0, s7, 0xe000
	s_nop 0
	global_load_lds_dwordx4 v[194:195], off
	s_waitcnt vmcnt(8)
	s_waitcnt lgkmcnt(0)
	s_barrier
	s_setprio 1
	v_mfma_f32_16x16x32_bf16 v[124:127], v[128:131], v[204:207], v[124:127]
	v_mfma_f32_16x16x32_bf16 v[120:123], v[164:167], v[204:207], v[120:123]
	v_mfma_f32_16x16x32_bf16 v[116:119], v[128:131], v[212:215], v[116:119]
	v_mfma_f32_16x16x32_bf16 v[112:115], v[164:167], v[212:215], v[112:115]
	v_mfma_f32_16x16x32_bf16 v[108:111], v[128:131], v[220:223], v[108:111]
	v_mfma_f32_16x16x32_bf16 v[104:107], v[164:167], v[220:223], v[104:107]
	v_mfma_f32_16x16x32_bf16 v[100:103], v[128:131], v[228:231], v[100:103]
	v_mfma_f32_16x16x32_bf16 v[96:99], v[164:167], v[228:231], v[96:99]
	v_mfma_f32_16x16x32_bf16 v[124:127], v[132:135], v[208:211], v[124:127]
	v_mfma_f32_16x16x32_bf16 v[120:123], v[168:171], v[208:211], v[120:123]
	v_mfma_f32_16x16x32_bf16 v[116:119], v[132:135], v[216:219], v[116:119]
	v_mfma_f32_16x16x32_bf16 v[112:115], v[168:171], v[216:219], v[112:115]
	v_mfma_f32_16x16x32_bf16 v[108:111], v[132:135], v[224:227], v[108:111]
	v_mfma_f32_16x16x32_bf16 v[104:107], v[168:171], v[224:227], v[104:107]
	v_mfma_f32_16x16x32_bf16 v[100:103], v[132:135], v[232:235], v[100:103]
	v_mfma_f32_16x16x32_bf16 v[96:99], v[168:171], v[232:235], v[96:99]
	s_setprio 0
	s_setprio 1
	v_mfma_f32_16x16x32_bf16 v[68:71], v[172:175], v[204:207], v[68:71]
	v_mfma_f32_16x16x32_bf16 v[60:63], v[190:193], v[204:207], v[60:63]
	v_mfma_f32_16x16x32_bf16 v[52:55], v[172:175], v[212:215], v[52:55]
	v_mfma_f32_16x16x32_bf16 v[48:51], v[190:193], v[212:215], v[48:51]
	v_mfma_f32_16x16x32_bf16 v[44:47], v[172:175], v[220:223], v[44:47]
	v_mfma_f32_16x16x32_bf16 v[40:43], v[190:193], v[220:223], v[40:43]
	v_mfma_f32_16x16x32_bf16 v[36:39], v[172:175], v[228:231], v[36:39]
	v_mfma_f32_16x16x32_bf16 v[32:35], v[190:193], v[228:231], v[32:35]
	v_mfma_f32_16x16x32_bf16 v[68:71], v[186:189], v[208:211], v[68:71]
	v_mfma_f32_16x16x32_bf16 v[60:63], v[200:203], v[208:211], v[60:63]
	v_mfma_f32_16x16x32_bf16 v[52:55], v[186:189], v[216:219], v[52:55]
	v_mfma_f32_16x16x32_bf16 v[48:51], v[200:203], v[216:219], v[48:51]
	v_mfma_f32_16x16x32_bf16 v[44:47], v[186:189], v[224:227], v[44:47]
	v_mfma_f32_16x16x32_bf16 v[40:43], v[200:203], v[224:227], v[40:43]
	v_mfma_f32_16x16x32_bf16 v[36:39], v[186:189], v[232:235], v[36:39]
	v_mfma_f32_16x16x32_bf16 v[32:35], v[200:203], v[232:235], v[32:35]
	s_setprio 0
	s_barrier
	s_add_i32 s64, s54, s33
	v_lshl_add_u64 v[194:195], s[4:5], 0, v[138:139]
	s_mov_b32 m0, s64
	ds_read_b128 v[204:207], v182 offset:16384
	ds_read_b128 v[208:211], v182 offset:17408
	ds_read_b128 v[212:215], v182 offset:18432
	ds_read_b128 v[216:219], v182 offset:19456
	ds_read_b128 v[220:223], v182 offset:20480
	ds_read_b128 v[224:227], v182 offset:21504
	ds_read_b128 v[228:231], v182 offset:22528
	ds_read_b128 v[232:235], v182 offset:23552
	global_load_lds_dwordx4 v[194:195], off
	s_add_i32 m0, s64, 0x2000
	s_add_u32 s64, s4, 0x40000
	v_lshl_add_u64 v[236:237], s[4:5], 0, v[142:143]
	s_addc_u32 s65, s5, 0
	s_add_i32 s66, s55, s33
	global_load_lds_dwordx4 v[236:237], off
	v_lshl_add_u64 v[238:239], s[64:65], 0, v[138:139]
	s_mov_b32 m0, s66
	v_lshl_add_u64 v[240:241], s[42:43], 0, v[140:141]
	global_load_lds_dwordx4 v[238:239], off
	v_lshl_add_u64 v[238:239], s[64:65], 0, v[142:143]
	s_add_i32 m0, s66, 0x2000
	s_nop 0
	global_load_lds_dwordx4 v[238:239], off
	v_lshl_add_u64 v[238:239], s[42:43], 0, v[136:137]
	s_mov_b32 m0, s7
	s_nop 0
	global_load_lds_dwordx4 v[238:239], off
	s_mov_b32 m0, s44
	s_nop 0
	global_load_lds_dwordx4 v[240:241], off
	s_waitcnt vmcnt(8)
	s_waitcnt lgkmcnt(0)
	s_barrier
	s_setprio 1
	v_mfma_f32_16x16x32_bf16 v[92:95], v[128:131], v[204:207], v[92:95]
	v_mfma_f32_16x16x32_bf16 v[88:91], v[164:167], v[204:207], v[88:91]
	v_mfma_f32_16x16x32_bf16 v[84:87], v[128:131], v[212:215], v[84:87]
	v_mfma_f32_16x16x32_bf16 v[80:83], v[164:167], v[212:215], v[80:83]
	v_mfma_f32_16x16x32_bf16 v[76:79], v[128:131], v[220:223], v[76:79]
	v_mfma_f32_16x16x32_bf16 v[72:75], v[164:167], v[220:223], v[72:75]
	v_mfma_f32_16x16x32_bf16 v[64:67], v[128:131], v[228:231], v[64:67]
	v_mfma_f32_16x16x32_bf16 v[56:59], v[164:167], v[228:231], v[56:59]
	v_mfma_f32_16x16x32_bf16 v[92:95], v[132:135], v[208:211], v[92:95]
	v_mfma_f32_16x16x32_bf16 v[88:91], v[168:171], v[208:211], v[88:91]
	v_mfma_f32_16x16x32_bf16 v[84:87], v[132:135], v[216:219], v[84:87]
	v_mfma_f32_16x16x32_bf16 v[80:83], v[168:171], v[216:219], v[80:83]
	v_mfma_f32_16x16x32_bf16 v[76:79], v[132:135], v[224:227], v[76:79]
	v_mfma_f32_16x16x32_bf16 v[72:75], v[168:171], v[224:227], v[72:75]
	v_mfma_f32_16x16x32_bf16 v[64:67], v[132:135], v[232:235], v[64:67]
	v_mfma_f32_16x16x32_bf16 v[56:59], v[168:171], v[232:235], v[56:59]
	s_setprio 0
	s_setprio 1
	v_mfma_f32_16x16x32_bf16 v[28:31], v[172:175], v[204:207], v[28:31]
	v_mfma_f32_16x16x32_bf16 v[24:27], v[190:193], v[204:207], v[24:27]
	v_mfma_f32_16x16x32_bf16 v[20:23], v[172:175], v[212:215], v[20:23]
	v_mfma_f32_16x16x32_bf16 v[16:19], v[190:193], v[212:215], v[16:19]
	v_mfma_f32_16x16x32_bf16 v[12:15], v[172:175], v[220:223], v[12:15]
	v_mfma_f32_16x16x32_bf16 v[8:11], v[190:193], v[220:223], v[8:11]
	v_mfma_f32_16x16x32_bf16 v[4:7], v[172:175], v[228:231], v[4:7]
	v_mfma_f32_16x16x32_bf16 v[0:3], v[190:193], v[228:231], v[0:3]
	v_mfma_f32_16x16x32_bf16 v[28:31], v[186:189], v[208:211], v[28:31]
	v_mfma_f32_16x16x32_bf16 v[24:27], v[200:203], v[208:211], v[24:27]
	v_mfma_f32_16x16x32_bf16 v[20:23], v[186:189], v[216:219], v[20:23]
	v_mfma_f32_16x16x32_bf16 v[16:19], v[200:203], v[216:219], v[16:19]
	v_mfma_f32_16x16x32_bf16 v[12:15], v[186:189], v[224:227], v[12:15]
	v_mfma_f32_16x16x32_bf16 v[8:11], v[200:203], v[224:227], v[8:11]
	v_mfma_f32_16x16x32_bf16 v[4:7], v[186:189], v[232:235], v[4:7]
	v_mfma_f32_16x16x32_bf16 v[0:3], v[200:203], v[232:235], v[0:3]
	s_setprio 0
	s_barrier
	s_add_i32 s64, 0, 0x18000
	v_add_u32_e32 v144, s64, v176
	s_add_i32 s65, 0, 0x1c000
	ds_read_b128 v[128:131], v144
	ds_read_b128 v[132:135], v144 offset:1024
	ds_read_b128 v[164:167], v144 offset:2048
	ds_read_b128 v[168:171], v144 offset:3072
	v_add_u32_e32 v144, s65, v176
	ds_read_b128 v[172:175], v144
	ds_read_b128 v[186:189], v144 offset:1024
	ds_read_b128 v[190:193], v144 offset:2048
	ds_read_b128 v[200:203], v144 offset:3072
	s_add_u32 s42, s42, 0x40000
	s_addc_u32 s43, s43, 0
	s_mov_b32 m0, s45
	v_lshl_add_u64 v[242:243], s[42:43], 0, v[136:137]
	ds_read_b128 v[204:207], v182 offset:32768
	ds_read_b128 v[208:211], v182 offset:33792
	ds_read_b128 v[212:215], v182 offset:34816
	ds_read_b128 v[216:219], v182 offset:35840
	ds_read_b128 v[220:223], v182 offset:36864
	ds_read_b128 v[224:227], v182 offset:37888
	ds_read_b128 v[228:231], v182 offset:38912
	ds_read_b128 v[232:235], v182 offset:39936
	global_load_lds_dwordx4 v[242:243], off
	v_lshl_add_u64 v[242:243], s[42:43], 0, v[140:141]
	s_mov_b32 m0, s46
	s_nop 0
	global_load_lds_dwordx4 v[242:243], off
	s_waitcnt vmcnt(8)
	s_waitcnt lgkmcnt(0)
	s_barrier
	s_setprio 1
	v_mfma_f32_16x16x32_bf16 v[124:127], v[128:131], v[204:207], v[124:127]
	v_mfma_f32_16x16x32_bf16 v[120:123], v[164:167], v[204:207], v[120:123]
	v_mfma_f32_16x16x32_bf16 v[116:119], v[128:131], v[212:215], v[116:119]
	v_mfma_f32_16x16x32_bf16 v[112:115], v[164:167], v[212:215], v[112:115]
	v_mfma_f32_16x16x32_bf16 v[108:111], v[128:131], v[220:223], v[108:111]
	v_mfma_f32_16x16x32_bf16 v[104:107], v[164:167], v[220:223], v[104:107]
	v_mfma_f32_16x16x32_bf16 v[100:103], v[128:131], v[228:231], v[100:103]
	v_mfma_f32_16x16x32_bf16 v[96:99], v[164:167], v[228:231], v[96:99]
	v_mfma_f32_16x16x32_bf16 v[124:127], v[132:135], v[208:211], v[124:127]
	v_mfma_f32_16x16x32_bf16 v[120:123], v[168:171], v[208:211], v[120:123]
	v_mfma_f32_16x16x32_bf16 v[116:119], v[132:135], v[216:219], v[116:119]
	v_mfma_f32_16x16x32_bf16 v[112:115], v[168:171], v[216:219], v[112:115]
	v_mfma_f32_16x16x32_bf16 v[108:111], v[132:135], v[224:227], v[108:111]
	v_mfma_f32_16x16x32_bf16 v[104:107], v[168:171], v[224:227], v[104:107]
	v_mfma_f32_16x16x32_bf16 v[100:103], v[132:135], v[232:235], v[100:103]
	v_mfma_f32_16x16x32_bf16 v[96:99], v[168:171], v[232:235], v[96:99]
	s_setprio 0
	s_setprio 1
	v_mfma_f32_16x16x32_bf16 v[68:71], v[172:175], v[204:207], v[68:71]
	v_mfma_f32_16x16x32_bf16 v[60:63], v[190:193], v[204:207], v[60:63]
	v_mfma_f32_16x16x32_bf16 v[52:55], v[172:175], v[212:215], v[52:55]
	v_mfma_f32_16x16x32_bf16 v[48:51], v[190:193], v[212:215], v[48:51]
	v_mfma_f32_16x16x32_bf16 v[44:47], v[172:175], v[220:223], v[44:47]
	v_mfma_f32_16x16x32_bf16 v[40:43], v[190:193], v[220:223], v[40:43]
	v_mfma_f32_16x16x32_bf16 v[36:39], v[172:175], v[228:231], v[36:39]
	v_mfma_f32_16x16x32_bf16 v[32:35], v[190:193], v[228:231], v[32:35]
	v_mfma_f32_16x16x32_bf16 v[68:71], v[186:189], v[208:211], v[68:71]
	v_mfma_f32_16x16x32_bf16 v[60:63], v[200:203], v[208:211], v[60:63]
	v_mfma_f32_16x16x32_bf16 v[52:55], v[186:189], v[216:219], v[52:55]
	v_mfma_f32_16x16x32_bf16 v[48:51], v[200:203], v[216:219], v[48:51]
	v_mfma_f32_16x16x32_bf16 v[44:47], v[186:189], v[224:227], v[44:47]
	v_mfma_f32_16x16x32_bf16 v[40:43], v[200:203], v[224:227], v[40:43]
	v_mfma_f32_16x16x32_bf16 v[36:39], v[186:189], v[232:235], v[36:39]
	v_mfma_f32_16x16x32_bf16 v[32:35], v[200:203], v[232:235], v[32:35]
	s_setprio 0
	s_barrier
	s_add_i32 s42, s64, s33
	v_lshl_add_u64 v[194:195], v[194:195], 0, s[20:21]
	s_mov_b32 m0, s42
	ds_read_b128 v[204:207], v182 offset:49152
	ds_read_b128 v[208:211], v182 offset:50176
	ds_read_b128 v[212:215], v182 offset:51200
	ds_read_b128 v[216:219], v182 offset:52224
	ds_read_b128 v[220:223], v182 offset:53248
	ds_read_b128 v[224:227], v182 offset:54272
	ds_read_b128 v[228:231], v182 offset:55296
	ds_read_b128 v[232:235], v182 offset:56320
	global_load_lds_dwordx4 v[194:195], off
	s_add_i32 m0, s42, 0x2000
	s_add_u32 s4, s4, 0x40080
	v_lshl_add_u64 v[194:195], v[236:237], 0, s[20:21]
	s_addc_u32 s5, s5, 0
	s_add_i32 s42, s65, s33
	global_load_lds_dwordx4 v[194:195], off
	v_lshl_add_u64 v[194:195], s[4:5], 0, v[138:139]
	s_mov_b32 m0, s42
	s_nop 0
	global_load_lds_dwordx4 v[194:195], off
	v_lshl_add_u64 v[194:195], s[4:5], 0, v[142:143]
	s_add_i32 m0, s42, 0x2000
	s_nop 0
	global_load_lds_dwordx4 v[194:195], off
	v_lshl_add_u64 v[194:195], v[238:239], 0, s[20:21]
	s_mov_b32 m0, s49
	s_nop 0
	global_load_lds_dwordx4 v[194:195], off
	v_lshl_add_u64 v[194:195], v[240:241], 0, s[20:21]
	s_mov_b32 m0, s50
	s_nop 0
	global_load_lds_dwordx4 v[194:195], off
	s_waitcnt vmcnt(8)
	s_waitcnt lgkmcnt(0)
	s_barrier
	s_setprio 1
	v_mfma_f32_16x16x32_bf16 v[92:95], v[128:131], v[204:207], v[92:95]
	v_mfma_f32_16x16x32_bf16 v[88:91], v[164:167], v[204:207], v[88:91]
	v_mfma_f32_16x16x32_bf16 v[84:87], v[128:131], v[212:215], v[84:87]
	v_mfma_f32_16x16x32_bf16 v[80:83], v[164:167], v[212:215], v[80:83]
	v_mfma_f32_16x16x32_bf16 v[76:79], v[128:131], v[220:223], v[76:79]
	v_mfma_f32_16x16x32_bf16 v[72:75], v[164:167], v[220:223], v[72:75]
	v_mfma_f32_16x16x32_bf16 v[64:67], v[128:131], v[228:231], v[64:67]
	v_mfma_f32_16x16x32_bf16 v[56:59], v[164:167], v[228:231], v[56:59]
	v_mfma_f32_16x16x32_bf16 v[92:95], v[132:135], v[208:211], v[92:95]
	v_mfma_f32_16x16x32_bf16 v[88:91], v[168:171], v[208:211], v[88:91]
	v_mfma_f32_16x16x32_bf16 v[84:87], v[132:135], v[216:219], v[84:87]
	v_mfma_f32_16x16x32_bf16 v[80:83], v[168:171], v[216:219], v[80:83]
	v_mfma_f32_16x16x32_bf16 v[76:79], v[132:135], v[224:227], v[76:79]
	v_mfma_f32_16x16x32_bf16 v[72:75], v[168:171], v[224:227], v[72:75]
	v_mfma_f32_16x16x32_bf16 v[64:67], v[132:135], v[232:235], v[64:67]
	v_mfma_f32_16x16x32_bf16 v[56:59], v[168:171], v[232:235], v[56:59]
	s_setprio 0
	s_setprio 1
	v_mfma_f32_16x16x32_bf16 v[28:31], v[172:175], v[204:207], v[28:31]
	v_mfma_f32_16x16x32_bf16 v[24:27], v[190:193], v[204:207], v[24:27]
	v_mfma_f32_16x16x32_bf16 v[20:23], v[172:175], v[212:215], v[20:23]
	v_mfma_f32_16x16x32_bf16 v[16:19], v[190:193], v[212:215], v[16:19]
	v_mfma_f32_16x16x32_bf16 v[12:15], v[172:175], v[220:223], v[12:15]
	v_mfma_f32_16x16x32_bf16 v[8:11], v[190:193], v[220:223], v[8:11]
	v_mfma_f32_16x16x32_bf16 v[4:7], v[172:175], v[228:231], v[4:7]
	v_mfma_f32_16x16x32_bf16 v[0:3], v[190:193], v[228:231], v[0:3]
	v_mfma_f32_16x16x32_bf16 v[28:31], v[186:189], v[208:211], v[28:31]
	v_mfma_f32_16x16x32_bf16 v[24:27], v[200:203], v[208:211], v[24:27]
	v_mfma_f32_16x16x32_bf16 v[20:23], v[186:189], v[216:219], v[20:23]
	v_mfma_f32_16x16x32_bf16 v[16:19], v[200:203], v[216:219], v[16:19]
	v_mfma_f32_16x16x32_bf16 v[12:15], v[186:189], v[224:227], v[12:15]
	v_mfma_f32_16x16x32_bf16 v[8:11], v[200:203], v[224:227], v[8:11]
	v_mfma_f32_16x16x32_bf16 v[4:7], v[186:189], v[232:235], v[4:7]
	v_mfma_f32_16x16x32_bf16 v[0:3], v[200:203], v[232:235], v[0:3]
	s_setprio 0
	s_barrier
	s_add_i32 s63, s63, 2
	s_add_u32 s0, s0, 0x100
	s_addc_u32 s1, s1, 0
	s_add_u32 s61, s61, 0x100
	s_addc_u32 s62, s62, 0
	s_cmp_gt_u32 s63, 13
	s_cbranch_scc0 .LBB0_730
	s_and_b64 vcc, exec, s[22:23]
	s_cbranch_vccz .LBB0_733
	s_barrier

.LBB0_881:
	ds_read_b128 v[150:153], v147
	ds_read_b128 v[154:157], v147 offset:1024
	ds_read_b128 v[158:161], v147 offset:2048
	ds_read_b128 v[162:165], v147 offset:3072
	ds_read_b128 v[166:169], v148
	ds_read_b128 v[170:173], v148 offset:1024
	ds_read_b128 v[174:177], v148 offset:2048
	ds_read_b128 v[178:181], v148 offset:3072
	s_add_u32 s20, s18, 0xfffc0080
	s_addc_u32 s21, s19, -1
	s_cmp_eq_u32 s44, 12
	s_cselect_b32 s23, s11, s21
	s_cselect_b32 s22, s40, s20
	s_cselect_b32 s21, s9, s43
	s_cselect_b32 s20, s41, s42
	v_lshl_add_u64 v[194:195], s[18:19], 0, v[136:137]
	s_add_i32 m0, s17, 0xc000
	ds_read_b128 v[182:185], v149
	ds_read_b128 v[186:189], v149 offset:1024
	ds_read_b128 v[190:193], v149 offset:2048
	ds_read_b128 v[200:203], v149 offset:3072
	ds_read_b128 v[204:207], v149 offset:4096
	ds_read_b128 v[208:211], v149 offset:5120
	ds_read_b128 v[212:215], v149 offset:6144
	ds_read_b128 v[216:219], v149 offset:7168
	global_load_lds_dwordx4 v[194:195], off
	v_lshl_add_u64 v[194:195], s[18:19], 0, v[138:139]
	s_add_i32 m0, s17, 0xe000
	s_nop 0
	global_load_lds_dwordx4 v[194:195], off
	s_waitcnt vmcnt(8)
	s_waitcnt lgkmcnt(0)
	s_barrier
	s_setprio 1
	v_mfma_f32_16x16x32_bf16 v[124:127], v[150:153], v[182:185], v[124:127]
	v_mfma_f32_16x16x32_bf16 v[120:123], v[158:161], v[182:185], v[120:123]
	v_mfma_f32_16x16x32_bf16 v[108:111], v[150:153], v[190:193], v[108:111]
	v_mfma_f32_16x16x32_bf16 v[104:107], v[158:161], v[190:193], v[104:107]
	v_mfma_f32_16x16x32_bf16 v[92:95], v[150:153], v[204:207], v[92:95]
	v_mfma_f32_16x16x32_bf16 v[88:91], v[158:161], v[204:207], v[88:91]
	v_mfma_f32_16x16x32_bf16 v[76:79], v[150:153], v[212:215], v[76:79]
	v_mfma_f32_16x16x32_bf16 v[72:75], v[158:161], v[212:215], v[72:75]
	v_mfma_f32_16x16x32_bf16 v[124:127], v[154:157], v[186:189], v[124:127]
	v_mfma_f32_16x16x32_bf16 v[120:123], v[162:165], v[186:189], v[120:123]
	v_mfma_f32_16x16x32_bf16 v[108:111], v[154:157], v[200:203], v[108:111]
	v_mfma_f32_16x16x32_bf16 v[104:107], v[162:165], v[200:203], v[104:107]
	v_mfma_f32_16x16x32_bf16 v[92:95], v[154:157], v[208:211], v[92:95]
	v_mfma_f32_16x16x32_bf16 v[88:91], v[162:165], v[208:211], v[88:91]
	v_mfma_f32_16x16x32_bf16 v[76:79], v[154:157], v[216:219], v[76:79]
	v_mfma_f32_16x16x32_bf16 v[72:75], v[162:165], v[216:219], v[72:75]
	s_setprio 0
	s_setprio 1
	v_mfma_f32_16x16x32_bf16 v[116:119], v[166:169], v[182:185], v[116:119]
	v_mfma_f32_16x16x32_bf16 v[112:115], v[174:177], v[182:185], v[112:115]
	v_mfma_f32_16x16x32_bf16 v[100:103], v[166:169], v[190:193], v[100:103]
	v_mfma_f32_16x16x32_bf16 v[96:99], v[174:177], v[190:193], v[96:99]
	v_mfma_f32_16x16x32_bf16 v[84:87], v[166:169], v[204:207], v[84:87]
	v_mfma_f32_16x16x32_bf16 v[80:83], v[174:177], v[204:207], v[80:83]
	v_mfma_f32_16x16x32_bf16 v[68:71], v[166:169], v[212:215], v[68:71]
	v_mfma_f32_16x16x32_bf16 v[64:67], v[174:177], v[212:215], v[64:67]
	v_mfma_f32_16x16x32_bf16 v[116:119], v[170:173], v[186:189], v[116:119]
	v_mfma_f32_16x16x32_bf16 v[112:115], v[178:181], v[186:189], v[112:115]
	v_mfma_f32_16x16x32_bf16 v[100:103], v[170:173], v[200:203], v[100:103]
	v_mfma_f32_16x16x32_bf16 v[96:99], v[178:181], v[200:203], v[96:99]
	v_mfma_f32_16x16x32_bf16 v[84:87], v[170:173], v[208:211], v[84:87]
	v_mfma_f32_16x16x32_bf16 v[80:83], v[178:181], v[208:211], v[80:83]
	v_mfma_f32_16x16x32_bf16 v[68:71], v[170:173], v[216:219], v[68:71]
	v_mfma_f32_16x16x32_bf16 v[64:67], v[178:181], v[216:219], v[64:67]
	s_setprio 0
	s_barrier
	s_add_i32 s45, s36, s24
	v_lshl_add_u64 v[194:195], s[20:21], 0, v[132:133]
	s_mov_b32 m0, s45
	ds_read_b128 v[182:185], v149 offset:16384
	ds_read_b128 v[186:189], v149 offset:17408
	ds_read_b128 v[190:193], v149 offset:18432
	ds_read_b128 v[200:203], v149 offset:19456
	ds_read_b128 v[204:207], v149 offset:20480
	ds_read_b128 v[208:211], v149 offset:21504
	ds_read_b128 v[212:215], v149 offset:22528
	ds_read_b128 v[216:219], v149 offset:23552
	global_load_lds_dwordx4 v[194:195], off
	s_add_i32 m0, s45, 0x2000
	s_add_u32 s46, s20, 0x40000
	v_lshl_add_u64 v[220:221], s[20:21], 0, v[128:129]
	s_addc_u32 s47, s21, 0
	s_add_i32 s45, s37, s24
	global_load_lds_dwordx4 v[220:221], off
	v_lshl_add_u64 v[222:223], s[46:47], 0, v[132:133]
	s_mov_b32 m0, s45
	v_lshl_add_u64 v[224:225], s[22:23], 0, v[130:131]
	global_load_lds_dwordx4 v[222:223], off
	v_lshl_add_u64 v[222:223], s[46:47], 0, v[128:129]
	s_add_i32 m0, s45, 0x2000
	s_nop 0
	global_load_lds_dwordx4 v[222:223], off
	v_lshl_add_u64 v[222:223], s[22:23], 0, v[134:135]
	s_mov_b32 m0, s17
	s_nop 0
	global_load_lds_dwordx4 v[222:223], off
	s_mov_b32 m0, s27
	s_nop 0
	global_load_lds_dwordx4 v[224:225], off
	s_waitcnt vmcnt(8)
	s_waitcnt lgkmcnt(0)
	s_barrier
	s_setprio 1
	v_mfma_f32_16x16x32_bf16 v[60:63], v[150:153], v[182:185], v[60:63]
	v_mfma_f32_16x16x32_bf16 v[56:59], v[158:161], v[182:185], v[56:59]
	v_mfma_f32_16x16x32_bf16 v[44:47], v[150:153], v[190:193], v[44:47]
	v_mfma_f32_16x16x32_bf16 v[40:43], v[158:161], v[190:193], v[40:43]
	v_mfma_f32_16x16x32_bf16 v[28:31], v[150:153], v[204:207], v[28:31]
	v_mfma_f32_16x16x32_bf16 v[24:27], v[158:161], v[204:207], v[24:27]
	v_mfma_f32_16x16x32_bf16 v[12:15], v[150:153], v[212:215], v[12:15]
	v_mfma_f32_16x16x32_bf16 v[8:11], v[158:161], v[212:215], v[8:11]
	v_mfma_f32_16x16x32_bf16 v[60:63], v[154:157], v[186:189], v[60:63]
	v_mfma_f32_16x16x32_bf16 v[56:59], v[162:165], v[186:189], v[56:59]
	v_mfma_f32_16x16x32_bf16 v[44:47], v[154:157], v[200:203], v[44:47]
	v_mfma_f32_16x16x32_bf16 v[40:43], v[162:165], v[200:203], v[40:43]
	v_mfma_f32_16x16x32_bf16 v[28:31], v[154:157], v[208:211], v[28:31]
	v_mfma_f32_16x16x32_bf16 v[24:27], v[162:165], v[208:211], v[24:27]
	v_mfma_f32_16x16x32_bf16 v[12:15], v[154:157], v[216:219], v[12:15]
	v_mfma_f32_16x16x32_bf16 v[8:11], v[162:165], v[216:219], v[8:11]
	s_setprio 0
	s_setprio 1
	v_mfma_f32_16x16x32_bf16 v[52:55], v[166:169], v[182:185], v[52:55]
	v_mfma_f32_16x16x32_bf16 v[48:51], v[174:177], v[182:185], v[48:51]
	v_mfma_f32_16x16x32_bf16 v[36:39], v[166:169], v[190:193], v[36:39]
	v_mfma_f32_16x16x32_bf16 v[32:35], v[174:177], v[190:193], v[32:35]
	v_mfma_f32_16x16x32_bf16 v[20:23], v[166:169], v[204:207], v[20:23]
	v_mfma_f32_16x16x32_bf16 v[16:19], v[174:177], v[204:207], v[16:19]
	v_mfma_f32_16x16x32_bf16 v[4:7], v[166:169], v[212:215], v[4:7]
	v_mfma_f32_16x16x32_bf16 v[0:3], v[174:177], v[212:215], v[0:3]
	v_mfma_f32_16x16x32_bf16 v[52:55], v[170:173], v[186:189], v[52:55]
	v_mfma_f32_16x16x32_bf16 v[48:51], v[178:181], v[186:189], v[48:51]
	v_mfma_f32_16x16x32_bf16 v[36:39], v[170:173], v[200:203], v[36:39]
	v_mfma_f32_16x16x32_bf16 v[32:35], v[178:181], v[200:203], v[32:35]
	v_mfma_f32_16x16x32_bf16 v[20:23], v[170:173], v[208:211], v[20:23]
	v_mfma_f32_16x16x32_bf16 v[16:19], v[178:181], v[208:211], v[16:19]
	v_mfma_f32_16x16x32_bf16 v[4:7], v[170:173], v[216:219], v[4:7]
	v_mfma_f32_16x16x32_bf16 v[0:3], v[178:181], v[216:219], v[0:3]
	s_setprio 0
	s_barrier
	s_add_i32 s45, 0, 0x18000
	s_add_i32 s46, 0, 0x1c000
	v_add_u32_e32 v162, s45, v145
	v_add_u32_e32 v178, s46, v145
	ds_read_b128 v[150:153], v162
	ds_read_b128 v[154:157], v162 offset:1024
	ds_read_b128 v[158:161], v162 offset:2048
	ds_read_b128 v[162:165], v162 offset:3072
	ds_read_b128 v[166:169], v178
	ds_read_b128 v[170:173], v178 offset:1024
	ds_read_b128 v[174:177], v178 offset:2048
	ds_read_b128 v[178:181], v178 offset:3072
	s_add_u32 s22, s22, 0x40000
	s_addc_u32 s23, s23, 0
	s_mov_b32 m0, s28
	v_lshl_add_u64 v[226:227], s[22:23], 0, v[134:135]
	ds_read_b128 v[182:185], v149 offset:32768
	ds_read_b128 v[186:189], v149 offset:33792
	ds_read_b128 v[190:193], v149 offset:34816
	ds_read_b128 v[200:203], v149 offset:35840
	ds_read_b128 v[204:207], v149 offset:36864
	ds_read_b128 v[208:211], v149 offset:37888
	ds_read_b128 v[212:215], v149 offset:38912
	ds_read_b128 v[216:219], v149 offset:39936
	global_load_lds_dwordx4 v[226:227], off
	v_lshl_add_u64 v[226:227], s[22:23], 0, v[130:131]
	s_mov_b32 m0, s29
	s_nop 0
	global_load_lds_dwordx4 v[226:227], off
	s_waitcnt vmcnt(8)
	s_waitcnt lgkmcnt(0)
	s_barrier
	s_setprio 1
	v_mfma_f32_16x16x32_bf16 v[124:127], v[150:153], v[182:185], v[124:127]
	v_mfma_f32_16x16x32_bf16 v[120:123], v[158:161], v[182:185], v[120:123]
	v_mfma_f32_16x16x32_bf16 v[108:111], v[150:153], v[190:193], v[108:111]
	v_mfma_f32_16x16x32_bf16 v[104:107], v[158:161], v[190:193], v[104:107]
	v_mfma_f32_16x16x32_bf16 v[92:95], v[150:153], v[204:207], v[92:95]
	v_mfma_f32_16x16x32_bf16 v[88:91], v[158:161], v[204:207], v[88:91]
	v_mfma_f32_16x16x32_bf16 v[76:79], v[150:153], v[212:215], v[76:79]
	v_mfma_f32_16x16x32_bf16 v[72:75], v[158:161], v[212:215], v[72:75]
	v_mfma_f32_16x16x32_bf16 v[124:127], v[154:157], v[186:189], v[124:127]
	v_mfma_f32_16x16x32_bf16 v[120:123], v[162:165], v[186:189], v[120:123]
	v_mfma_f32_16x16x32_bf16 v[108:111], v[154:157], v[200:203], v[108:111]
	v_mfma_f32_16x16x32_bf16 v[104:107], v[162:165], v[200:203], v[104:107]
	v_mfma_f32_16x16x32_bf16 v[92:95], v[154:157], v[208:211], v[92:95]
	v_mfma_f32_16x16x32_bf16 v[88:91], v[162:165], v[208:211], v[88:91]
	v_mfma_f32_16x16x32_bf16 v[76:79], v[154:157], v[216:219], v[76:79]
	v_mfma_f32_16x16x32_bf16 v[72:75], v[162:165], v[216:219], v[72:75]
	s_setprio 0
	s_setprio 1
	v_mfma_f32_16x16x32_bf16 v[116:119], v[166:169], v[182:185], v[116:119]
	v_mfma_f32_16x16x32_bf16 v[112:115], v[174:177], v[182:185], v[112:115]
	v_mfma_f32_16x16x32_bf16 v[100:103], v[166:169], v[190:193], v[100:103]
	v_mfma_f32_16x16x32_bf16 v[96:99], v[174:177], v[190:193], v[96:99]
	v_mfma_f32_16x16x32_bf16 v[84:87], v[166:169], v[204:207], v[84:87]
	v_mfma_f32_16x16x32_bf16 v[80:83], v[174:177], v[204:207], v[80:83]
	v_mfma_f32_16x16x32_bf16 v[68:71], v[166:169], v[212:215], v[68:71]
	v_mfma_f32_16x16x32_bf16 v[64:67], v[174:177], v[212:215], v[64:67]
	v_mfma_f32_16x16x32_bf16 v[116:119], v[170:173], v[186:189], v[116:119]
	v_mfma_f32_16x16x32_bf16 v[112:115], v[178:181], v[186:189], v[112:115]
	v_mfma_f32_16x16x32_bf16 v[100:103], v[170:173], v[200:203], v[100:103]
	v_mfma_f32_16x16x32_bf16 v[96:99], v[178:181], v[200:203], v[96:99]
	v_mfma_f32_16x16x32_bf16 v[84:87], v[170:173], v[208:211], v[84:87]
	v_mfma_f32_16x16x32_bf16 v[80:83], v[178:181], v[208:211], v[80:83]
	v_mfma_f32_16x16x32_bf16 v[68:71], v[170:173], v[216:219], v[68:71]
	v_mfma_f32_16x16x32_bf16 v[64:67], v[178:181], v[216:219], v[64:67]
	s_setprio 0
	s_barrier
	s_add_i32 s22, s45, s24
	v_lshl_add_u64 v[194:195], v[194:195], 0, s[4:5]
	s_mov_b32 m0, s22
	ds_read_b128 v[182:185], v149 offset:49152
	ds_read_b128 v[186:189], v149 offset:50176
	ds_read_b128 v[190:193], v149 offset:51200
	ds_read_b128 v[200:203], v149 offset:52224
	ds_read_b128 v[204:207], v149 offset:53248
	ds_read_b128 v[208:211], v149 offset:54272
	ds_read_b128 v[212:215], v149 offset:55296
	ds_read_b128 v[216:219], v149 offset:56320
	global_load_lds_dwordx4 v[194:195], off
	s_add_i32 m0, s22, 0x2000
	s_add_u32 s20, s20, 0x40080
	v_lshl_add_u64 v[194:195], v[220:221], 0, s[4:5]
	s_addc_u32 s21, s21, 0
	s_add_i32 s22, s46, s24
	global_load_lds_dwordx4 v[194:195], off
	v_lshl_add_u64 v[194:195], s[20:21], 0, v[132:133]
	s_mov_b32 m0, s22
	s_nop 0
	global_load_lds_dwordx4 v[194:195], off
	v_lshl_add_u64 v[194:195], s[20:21], 0, v[128:129]
	s_add_i32 m0, s22, 0x2000
	s_nop 0
	global_load_lds_dwordx4 v[194:195], off
	v_lshl_add_u64 v[194:195], v[222:223], 0, s[4:5]
	s_mov_b32 m0, s33
	s_nop 0
	global_load_lds_dwordx4 v[194:195], off
	v_lshl_add_u64 v[194:195], v[224:225], 0, s[4:5]
	s_mov_b32 m0, s34
	s_nop 0
	global_load_lds_dwordx4 v[194:195], off
	s_waitcnt vmcnt(8)
	s_waitcnt lgkmcnt(0)
	s_barrier
	s_setprio 1
	v_mfma_f32_16x16x32_bf16 v[60:63], v[150:153], v[182:185], v[60:63]
	v_mfma_f32_16x16x32_bf16 v[56:59], v[158:161], v[182:185], v[56:59]
	v_mfma_f32_16x16x32_bf16 v[44:47], v[150:153], v[190:193], v[44:47]
	v_mfma_f32_16x16x32_bf16 v[40:43], v[158:161], v[190:193], v[40:43]
	v_mfma_f32_16x16x32_bf16 v[28:31], v[150:153], v[204:207], v[28:31]
	v_mfma_f32_16x16x32_bf16 v[24:27], v[158:161], v[204:207], v[24:27]
	v_mfma_f32_16x16x32_bf16 v[12:15], v[150:153], v[212:215], v[12:15]
	v_mfma_f32_16x16x32_bf16 v[8:11], v[158:161], v[212:215], v[8:11]
	v_mfma_f32_16x16x32_bf16 v[60:63], v[154:157], v[186:189], v[60:63]
	v_mfma_f32_16x16x32_bf16 v[56:59], v[162:165], v[186:189], v[56:59]
	v_mfma_f32_16x16x32_bf16 v[44:47], v[154:157], v[200:203], v[44:47]
	v_mfma_f32_16x16x32_bf16 v[40:43], v[162:165], v[200:203], v[40:43]
	v_mfma_f32_16x16x32_bf16 v[28:31], v[154:157], v[208:211], v[28:31]
	v_mfma_f32_16x16x32_bf16 v[24:27], v[162:165], v[208:211], v[24:27]
	v_mfma_f32_16x16x32_bf16 v[12:15], v[154:157], v[216:219], v[12:15]
	v_mfma_f32_16x16x32_bf16 v[8:11], v[162:165], v[216:219], v[8:11]
	s_setprio 0
	s_setprio 1
	v_mfma_f32_16x16x32_bf16 v[52:55], v[166:169], v[182:185], v[52:55]
	v_mfma_f32_16x16x32_bf16 v[48:51], v[174:177], v[182:185], v[48:51]
	v_mfma_f32_16x16x32_bf16 v[36:39], v[166:169], v[190:193], v[36:39]
	v_mfma_f32_16x16x32_bf16 v[32:35], v[174:177], v[190:193], v[32:35]
	v_mfma_f32_16x16x32_bf16 v[20:23], v[166:169], v[204:207], v[20:23]
	v_mfma_f32_16x16x32_bf16 v[16:19], v[174:177], v[204:207], v[16:19]
	v_mfma_f32_16x16x32_bf16 v[4:7], v[166:169], v[212:215], v[4:7]
	v_mfma_f32_16x16x32_bf16 v[0:3], v[174:177], v[212:215], v[0:3]
	v_mfma_f32_16x16x32_bf16 v[52:55], v[170:173], v[186:189], v[52:55]
	v_mfma_f32_16x16x32_bf16 v[48:51], v[178:181], v[186:189], v[48:51]
	v_mfma_f32_16x16x32_bf16 v[36:39], v[170:173], v[200:203], v[36:39]
	v_mfma_f32_16x16x32_bf16 v[32:35], v[178:181], v[200:203], v[32:35]
	v_mfma_f32_16x16x32_bf16 v[20:23], v[170:173], v[208:211], v[20:23]
	v_mfma_f32_16x16x32_bf16 v[16:19], v[178:181], v[208:211], v[16:19]
	v_mfma_f32_16x16x32_bf16 v[4:7], v[170:173], v[216:219], v[4:7]
	v_mfma_f32_16x16x32_bf16 v[0:3], v[178:181], v[216:219], v[0:3]
	s_setprio 0
	s_barrier
	s_add_i32 s44, s44, 2
	s_add_u32 s18, s18, 0x100
	s_addc_u32 s19, s19, 0
	s_add_u32 s42, s42, 0x100
	s_addc_u32 s43, s43, 0
	s_cmp_gt_u32 s44, 13
	s_cbranch_scc0 .LBB0_881
	s_and_b64 vcc, exec, s[6:7]
	s_cbranch_vccz .LBB0_884
	s_barrier

.LBB0_964:
	ds_read_b128 v[128:131], v170
	ds_read_b128 v[132:135], v170 offset:1024
	ds_read_b128 v[156:159], v170 offset:2048
	ds_read_b128 v[160:163], v170 offset:3072
	ds_read_b128 v[176:179], v171
	ds_read_b128 v[180:183], v171 offset:1024
	ds_read_b128 v[184:187], v171 offset:2048
	ds_read_b128 v[188:191], v171 offset:3072
	s_add_u32 s4, s0, 0xfff50080
	s_addc_u32 s5, s1, -1
	s_cmp_eq_u32 s11, 40
	s_cselect_b32 s7, s51, s5
	s_cselect_b32 s6, s50, s4
	s_cselect_b32 s5, s53, s10
	s_cselect_b32 s4, s52, s9
	v_lshl_add_u64 v[196:197], s[0:1], 0, v[150:151]
	s_add_i32 m0, s60, 0xc000
	ds_read_b128 v[192:195], v172
	ds_read_b128 v[200:203], v172 offset:1024
	ds_read_b128 v[204:207], v172 offset:2048
	ds_read_b128 v[208:211], v172 offset:3072
	ds_read_b128 v[212:215], v172 offset:4096
	ds_read_b128 v[216:219], v172 offset:5120
	ds_read_b128 v[220:223], v172 offset:6144
	ds_read_b128 v[224:227], v172 offset:7168
	global_load_lds_dwordx4 v[196:197], off
	v_lshl_add_u64 v[196:197], s[0:1], 0, v[152:153]
	s_add_i32 m0, s60, 0xe000
	s_nop 0
	global_load_lds_dwordx4 v[196:197], off
	s_waitcnt vmcnt(8)
	s_waitcnt lgkmcnt(0)
	s_barrier
	s_setprio 1
	v_mfma_f32_16x16x32_bf16 v[124:127], v[128:131], v[192:195], v[124:127]
	v_mfma_f32_16x16x32_bf16 v[120:123], v[156:159], v[192:195], v[120:123]
	v_mfma_f32_16x16x32_bf16 v[116:119], v[128:131], v[204:207], v[116:119]
	v_mfma_f32_16x16x32_bf16 v[112:115], v[156:159], v[204:207], v[112:115]
	v_mfma_f32_16x16x32_bf16 v[108:111], v[128:131], v[212:215], v[108:111]
	v_mfma_f32_16x16x32_bf16 v[104:107], v[156:159], v[212:215], v[104:107]
	v_mfma_f32_16x16x32_bf16 v[100:103], v[128:131], v[220:223], v[100:103]
	v_mfma_f32_16x16x32_bf16 v[96:99], v[156:159], v[220:223], v[96:99]
	v_mfma_f32_16x16x32_bf16 v[124:127], v[132:135], v[200:203], v[124:127]
	v_mfma_f32_16x16x32_bf16 v[120:123], v[160:163], v[200:203], v[120:123]
	v_mfma_f32_16x16x32_bf16 v[116:119], v[132:135], v[208:211], v[116:119]
	v_mfma_f32_16x16x32_bf16 v[112:115], v[160:163], v[208:211], v[112:115]
	v_mfma_f32_16x16x32_bf16 v[108:111], v[132:135], v[216:219], v[108:111]
	v_mfma_f32_16x16x32_bf16 v[104:107], v[160:163], v[216:219], v[104:107]
	v_mfma_f32_16x16x32_bf16 v[100:103], v[132:135], v[224:227], v[100:103]
	v_mfma_f32_16x16x32_bf16 v[96:99], v[160:163], v[224:227], v[96:99]
	s_setprio 0
	s_setprio 1
	v_mfma_f32_16x16x32_bf16 v[60:63], v[176:179], v[192:195], v[60:63]
	v_mfma_f32_16x16x32_bf16 v[56:59], v[184:187], v[192:195], v[56:59]
	v_mfma_f32_16x16x32_bf16 v[52:55], v[176:179], v[204:207], v[52:55]
	v_mfma_f32_16x16x32_bf16 v[48:51], v[184:187], v[204:207], v[48:51]
	v_mfma_f32_16x16x32_bf16 v[44:47], v[176:179], v[212:215], v[44:47]
	v_mfma_f32_16x16x32_bf16 v[40:43], v[184:187], v[212:215], v[40:43]
	v_mfma_f32_16x16x32_bf16 v[36:39], v[176:179], v[220:223], v[36:39]
	v_mfma_f32_16x16x32_bf16 v[32:35], v[184:187], v[220:223], v[32:35]
	v_mfma_f32_16x16x32_bf16 v[60:63], v[180:183], v[200:203], v[60:63]
	v_mfma_f32_16x16x32_bf16 v[56:59], v[188:191], v[200:203], v[56:59]
	v_mfma_f32_16x16x32_bf16 v[52:55], v[180:183], v[208:211], v[52:55]
	v_mfma_f32_16x16x32_bf16 v[48:51], v[188:191], v[208:211], v[48:51]
	v_mfma_f32_16x16x32_bf16 v[44:47], v[180:183], v[216:219], v[44:47]
	v_mfma_f32_16x16x32_bf16 v[40:43], v[188:191], v[216:219], v[40:43]
	v_mfma_f32_16x16x32_bf16 v[36:39], v[180:183], v[224:227], v[36:39]
	v_mfma_f32_16x16x32_bf16 v[32:35], v[188:191], v[224:227], v[32:35]
	s_setprio 0
	s_barrier
	s_add_i32 s12, s70, s59
	v_lshl_add_u64 v[196:197], s[4:5], 0, v[138:139]
	s_mov_b32 m0, s12
	ds_read_b128 v[192:195], v172 offset:16384
	ds_read_b128 v[200:203], v172 offset:17408
	ds_read_b128 v[204:207], v172 offset:18432
	ds_read_b128 v[208:211], v172 offset:19456
	ds_read_b128 v[212:215], v172 offset:20480
	ds_read_b128 v[216:219], v172 offset:21504
	ds_read_b128 v[220:223], v172 offset:22528
	ds_read_b128 v[224:227], v172 offset:23552
	global_load_lds_dwordx4 v[196:197], off
	s_add_i32 m0, s12, 0x2000
	s_add_u32 s12, s4, 0xb0000
	v_lshl_add_u64 v[228:229], s[4:5], 0, v[142:143]
	s_addc_u32 s13, s5, 0
	s_add_i32 s14, s71, s59
	global_load_lds_dwordx4 v[228:229], off
	v_lshl_add_u64 v[230:231], s[12:13], 0, v[138:139]
	s_mov_b32 m0, s14
	v_lshl_add_u64 v[232:233], s[6:7], 0, v[140:141]
	global_load_lds_dwordx4 v[230:231], off
	v_lshl_add_u64 v[230:231], s[12:13], 0, v[142:143]
	s_add_i32 m0, s14, 0x2000
	s_nop 0
	global_load_lds_dwordx4 v[230:231], off
	v_lshl_add_u64 v[230:231], s[6:7], 0, v[136:137]
	s_mov_b32 m0, s60
	s_nop 0
	global_load_lds_dwordx4 v[230:231], off
	s_mov_b32 m0, s61
	s_nop 0
	global_load_lds_dwordx4 v[232:233], off
	s_waitcnt vmcnt(8)
	s_waitcnt lgkmcnt(0)
	s_barrier
	s_setprio 1
	v_mfma_f32_16x16x32_bf16 v[92:95], v[128:131], v[192:195], v[92:95]
	v_mfma_f32_16x16x32_bf16 v[88:91], v[156:159], v[192:195], v[88:91]
	v_mfma_f32_16x16x32_bf16 v[84:87], v[128:131], v[204:207], v[84:87]
	v_mfma_f32_16x16x32_bf16 v[80:83], v[156:159], v[204:207], v[80:83]
	v_mfma_f32_16x16x32_bf16 v[76:79], v[128:131], v[212:215], v[76:79]
	v_mfma_f32_16x16x32_bf16 v[72:75], v[156:159], v[212:215], v[72:75]
	v_mfma_f32_16x16x32_bf16 v[68:71], v[128:131], v[220:223], v[68:71]
	v_mfma_f32_16x16x32_bf16 v[64:67], v[156:159], v[220:223], v[64:67]
	v_mfma_f32_16x16x32_bf16 v[92:95], v[132:135], v[200:203], v[92:95]
	v_mfma_f32_16x16x32_bf16 v[88:91], v[160:163], v[200:203], v[88:91]
	v_mfma_f32_16x16x32_bf16 v[84:87], v[132:135], v[208:211], v[84:87]
	v_mfma_f32_16x16x32_bf16 v[80:83], v[160:163], v[208:211], v[80:83]
	v_mfma_f32_16x16x32_bf16 v[76:79], v[132:135], v[216:219], v[76:79]
	v_mfma_f32_16x16x32_bf16 v[72:75], v[160:163], v[216:219], v[72:75]
	v_mfma_f32_16x16x32_bf16 v[68:71], v[132:135], v[224:227], v[68:71]
	v_mfma_f32_16x16x32_bf16 v[64:67], v[160:163], v[224:227], v[64:67]
	s_setprio 0
	s_setprio 1
	v_mfma_f32_16x16x32_bf16 v[28:31], v[176:179], v[192:195], v[28:31]
	v_mfma_f32_16x16x32_bf16 v[24:27], v[184:187], v[192:195], v[24:27]
	v_mfma_f32_16x16x32_bf16 v[20:23], v[176:179], v[204:207], v[20:23]
	v_mfma_f32_16x16x32_bf16 v[16:19], v[184:187], v[204:207], v[16:19]
	v_mfma_f32_16x16x32_bf16 v[12:15], v[176:179], v[212:215], v[12:15]
	v_mfma_f32_16x16x32_bf16 v[8:11], v[184:187], v[212:215], v[8:11]
	v_mfma_f32_16x16x32_bf16 v[4:7], v[176:179], v[220:223], v[4:7]
	v_mfma_f32_16x16x32_bf16 v[0:3], v[184:187], v[220:223], v[0:3]
	v_mfma_f32_16x16x32_bf16 v[28:31], v[180:183], v[200:203], v[28:31]
	v_mfma_f32_16x16x32_bf16 v[24:27], v[188:191], v[200:203], v[24:27]
	v_mfma_f32_16x16x32_bf16 v[20:23], v[180:183], v[208:211], v[20:23]
	v_mfma_f32_16x16x32_bf16 v[16:19], v[188:191], v[208:211], v[16:19]
	v_mfma_f32_16x16x32_bf16 v[12:15], v[180:183], v[216:219], v[12:15]
	v_mfma_f32_16x16x32_bf16 v[8:11], v[188:191], v[216:219], v[8:11]
	v_mfma_f32_16x16x32_bf16 v[4:7], v[180:183], v[224:227], v[4:7]
	v_mfma_f32_16x16x32_bf16 v[0:3], v[188:191], v[224:227], v[0:3]
	s_setprio 0
	s_barrier
	s_add_i32 s12, 0, 0x18000
	s_add_i32 s13, 0, 0x1c000
	v_add_u32_e32 v160, s12, v166
	v_add_u32_e32 v188, s13, v166
	ds_read_b128 v[128:131], v160
	ds_read_b128 v[132:135], v160 offset:1024
	ds_read_b128 v[156:159], v160 offset:2048
	ds_read_b128 v[160:163], v160 offset:3072
	ds_read_b128 v[176:179], v188
	ds_read_b128 v[180:183], v188 offset:1024
	ds_read_b128 v[184:187], v188 offset:2048
	ds_read_b128 v[188:191], v188 offset:3072
	s_add_u32 s6, s6, 0xb0000
	s_addc_u32 s7, s7, 0
	s_mov_b32 m0, s62
	v_lshl_add_u64 v[234:235], s[6:7], 0, v[136:137]
	ds_read_b128 v[192:195], v172 offset:32768
	ds_read_b128 v[200:203], v172 offset:33792
	ds_read_b128 v[204:207], v172 offset:34816
	ds_read_b128 v[208:211], v172 offset:35840
	ds_read_b128 v[212:215], v172 offset:36864
	ds_read_b128 v[216:219], v172 offset:37888
	ds_read_b128 v[220:223], v172 offset:38912
	ds_read_b128 v[224:227], v172 offset:39936
	global_load_lds_dwordx4 v[234:235], off
	v_lshl_add_u64 v[234:235], s[6:7], 0, v[140:141]
	s_mov_b32 m0, s63
	s_nop 0
	global_load_lds_dwordx4 v[234:235], off
	s_waitcnt vmcnt(8)
	s_waitcnt lgkmcnt(0)
	s_barrier
	s_setprio 1
	v_mfma_f32_16x16x32_bf16 v[124:127], v[128:131], v[192:195], v[124:127]
	v_mfma_f32_16x16x32_bf16 v[120:123], v[156:159], v[192:195], v[120:123]
	v_mfma_f32_16x16x32_bf16 v[116:119], v[128:131], v[204:207], v[116:119]
	v_mfma_f32_16x16x32_bf16 v[112:115], v[156:159], v[204:207], v[112:115]
	v_mfma_f32_16x16x32_bf16 v[108:111], v[128:131], v[212:215], v[108:111]
	v_mfma_f32_16x16x32_bf16 v[104:107], v[156:159], v[212:215], v[104:107]
	v_mfma_f32_16x16x32_bf16 v[100:103], v[128:131], v[220:223], v[100:103]
	v_mfma_f32_16x16x32_bf16 v[96:99], v[156:159], v[220:223], v[96:99]
	v_mfma_f32_16x16x32_bf16 v[124:127], v[132:135], v[200:203], v[124:127]
	v_mfma_f32_16x16x32_bf16 v[120:123], v[160:163], v[200:203], v[120:123]
	v_mfma_f32_16x16x32_bf16 v[116:119], v[132:135], v[208:211], v[116:119]
	v_mfma_f32_16x16x32_bf16 v[112:115], v[160:163], v[208:211], v[112:115]
	v_mfma_f32_16x16x32_bf16 v[108:111], v[132:135], v[216:219], v[108:111]
	v_mfma_f32_16x16x32_bf16 v[104:107], v[160:163], v[216:219], v[104:107]
	v_mfma_f32_16x16x32_bf16 v[100:103], v[132:135], v[224:227], v[100:103]
	v_mfma_f32_16x16x32_bf16 v[96:99], v[160:163], v[224:227], v[96:99]
	s_setprio 0
	s_setprio 1
	v_mfma_f32_16x16x32_bf16 v[60:63], v[176:179], v[192:195], v[60:63]
	v_mfma_f32_16x16x32_bf16 v[56:59], v[184:187], v[192:195], v[56:59]
	v_mfma_f32_16x16x32_bf16 v[52:55], v[176:179], v[204:207], v[52:55]
	v_mfma_f32_16x16x32_bf16 v[48:51], v[184:187], v[204:207], v[48:51]
	v_mfma_f32_16x16x32_bf16 v[44:47], v[176:179], v[212:215], v[44:47]
	v_mfma_f32_16x16x32_bf16 v[40:43], v[184:187], v[212:215], v[40:43]
	v_mfma_f32_16x16x32_bf16 v[36:39], v[176:179], v[220:223], v[36:39]
	v_mfma_f32_16x16x32_bf16 v[32:35], v[184:187], v[220:223], v[32:35]
	v_mfma_f32_16x16x32_bf16 v[60:63], v[180:183], v[200:203], v[60:63]
	v_mfma_f32_16x16x32_bf16 v[56:59], v[188:191], v[200:203], v[56:59]
	v_mfma_f32_16x16x32_bf16 v[52:55], v[180:183], v[208:211], v[52:55]
	v_mfma_f32_16x16x32_bf16 v[48:51], v[188:191], v[208:211], v[48:51]
	v_mfma_f32_16x16x32_bf16 v[44:47], v[180:183], v[216:219], v[44:47]
	v_mfma_f32_16x16x32_bf16 v[40:43], v[188:191], v[216:219], v[40:43]
	v_mfma_f32_16x16x32_bf16 v[36:39], v[180:183], v[224:227], v[36:39]
	v_mfma_f32_16x16x32_bf16 v[32:35], v[188:191], v[224:227], v[32:35]
	s_setprio 0
	s_barrier
	s_add_i32 s6, s12, s59
	v_lshl_add_u64 v[196:197], v[196:197], 0, s[28:29]
	s_mov_b32 m0, s6
	ds_read_b128 v[192:195], v172 offset:49152
	ds_read_b128 v[200:203], v172 offset:50176
	ds_read_b128 v[204:207], v172 offset:51200
	ds_read_b128 v[208:211], v172 offset:52224
	ds_read_b128 v[212:215], v172 offset:53248
	ds_read_b128 v[216:219], v172 offset:54272
	ds_read_b128 v[220:223], v172 offset:55296
	ds_read_b128 v[224:227], v172 offset:56320
	global_load_lds_dwordx4 v[196:197], off
	s_add_i32 m0, s6, 0x2000
	s_add_u32 s4, s4, 0xb0080
	v_lshl_add_u64 v[196:197], v[228:229], 0, s[28:29]
	s_addc_u32 s5, s5, 0
	s_add_i32 s6, s13, s59
	global_load_lds_dwordx4 v[196:197], off
	v_lshl_add_u64 v[196:197], s[4:5], 0, v[138:139]
	s_mov_b32 m0, s6
	s_nop 0
	global_load_lds_dwordx4 v[196:197], off
	v_lshl_add_u64 v[196:197], s[4:5], 0, v[142:143]
	s_add_i32 m0, s6, 0x2000
	s_nop 0
	global_load_lds_dwordx4 v[196:197], off
	v_lshl_add_u64 v[196:197], v[230:231], 0, s[28:29]
	s_mov_b32 m0, s66
	s_nop 0
	global_load_lds_dwordx4 v[196:197], off
	v_lshl_add_u64 v[196:197], v[232:233], 0, s[28:29]
	s_mov_b32 m0, s67
	s_nop 0
	global_load_lds_dwordx4 v[196:197], off
	s_waitcnt vmcnt(8)
	s_waitcnt lgkmcnt(0)
	s_barrier
	s_setprio 1
	v_mfma_f32_16x16x32_bf16 v[92:95], v[128:131], v[192:195], v[92:95]
	v_mfma_f32_16x16x32_bf16 v[88:91], v[156:159], v[192:195], v[88:91]
	v_mfma_f32_16x16x32_bf16 v[84:87], v[128:131], v[204:207], v[84:87]
	v_mfma_f32_16x16x32_bf16 v[80:83], v[156:159], v[204:207], v[80:83]
	v_mfma_f32_16x16x32_bf16 v[76:79], v[128:131], v[212:215], v[76:79]
	v_mfma_f32_16x16x32_bf16 v[72:75], v[156:159], v[212:215], v[72:75]
	v_mfma_f32_16x16x32_bf16 v[68:71], v[128:131], v[220:223], v[68:71]
	v_mfma_f32_16x16x32_bf16 v[64:67], v[156:159], v[220:223], v[64:67]
	v_mfma_f32_16x16x32_bf16 v[92:95], v[132:135], v[200:203], v[92:95]
	v_mfma_f32_16x16x32_bf16 v[88:91], v[160:163], v[200:203], v[88:91]
	v_mfma_f32_16x16x32_bf16 v[84:87], v[132:135], v[208:211], v[84:87]
	v_mfma_f32_16x16x32_bf16 v[80:83], v[160:163], v[208:211], v[80:83]
	v_mfma_f32_16x16x32_bf16 v[76:79], v[132:135], v[216:219], v[76:79]
	v_mfma_f32_16x16x32_bf16 v[72:75], v[160:163], v[216:219], v[72:75]
	v_mfma_f32_16x16x32_bf16 v[68:71], v[132:135], v[224:227], v[68:71]
	v_mfma_f32_16x16x32_bf16 v[64:67], v[160:163], v[224:227], v[64:67]
	s_setprio 0
	s_setprio 1
	v_mfma_f32_16x16x32_bf16 v[28:31], v[176:179], v[192:195], v[28:31]
	v_mfma_f32_16x16x32_bf16 v[24:27], v[184:187], v[192:195], v[24:27]
	v_mfma_f32_16x16x32_bf16 v[20:23], v[176:179], v[204:207], v[20:23]
	v_mfma_f32_16x16x32_bf16 v[16:19], v[184:187], v[204:207], v[16:19]
	v_mfma_f32_16x16x32_bf16 v[12:15], v[176:179], v[212:215], v[12:15]
	v_mfma_f32_16x16x32_bf16 v[8:11], v[184:187], v[212:215], v[8:11]
	v_mfma_f32_16x16x32_bf16 v[4:7], v[176:179], v[220:223], v[4:7]
	v_mfma_f32_16x16x32_bf16 v[0:3], v[184:187], v[220:223], v[0:3]
	v_mfma_f32_16x16x32_bf16 v[28:31], v[180:183], v[200:203], v[28:31]
	v_mfma_f32_16x16x32_bf16 v[24:27], v[188:191], v[200:203], v[24:27]
	v_mfma_f32_16x16x32_bf16 v[20:23], v[180:183], v[208:211], v[20:23]
	v_mfma_f32_16x16x32_bf16 v[16:19], v[188:191], v[208:211], v[16:19]
	v_mfma_f32_16x16x32_bf16 v[12:15], v[180:183], v[216:219], v[12:15]
	v_mfma_f32_16x16x32_bf16 v[8:11], v[188:191], v[216:219], v[8:11]
	v_mfma_f32_16x16x32_bf16 v[4:7], v[180:183], v[224:227], v[4:7]
	v_mfma_f32_16x16x32_bf16 v[0:3], v[188:191], v[224:227], v[0:3]
	s_setprio 0
	s_barrier
	s_add_i32 s11, s11, 2
	s_add_u32 s0, s0, 0x100
	s_addc_u32 s1, s1, 0
	s_add_u32 s9, s9, 0x100
	s_addc_u32 s10, s10, 0
	s_cmp_gt_u32 s11, 41
	s_cbranch_scc0 .LBB0_964
	s_and_b64 vcc, exec, s[30:31]
	s_cbranch_vccz .LBB0_967
	s_barrier
